# p1 epilogue: rope table values prefetched once per tile; retention initial-state fragment loads batched 8 deep; remaining 4 barriers converted
# speedup vs baseline: 1.0653x; 1.0155x over previous
.LBB0_139:
	s_cmp_gt_u32 s67, 2
	s_cbranch_scc0 .LBB0_189
	s_waitcnt vmcnt(0)
	s_waitcnt vmcnt(63) expcnt(7) lgkmcnt(15)
	s_barrier
	s_mov_b64 s[4:5], exec
	v_readlane_b32 s2, v251, 3
	v_readlane_b32 s3, v251, 4
	s_and_b64 s[2:3], s[4:5], s[2:3]
	s_mov_b64 exec, s[2:3]
	s_cbranch_execz .Lxb_done_2
	v_mov_b32_e32 v0, 0
	s_waitcnt vmcnt(0) expcnt(0) lgkmcnt(0)
	ds_read_b32 v2, v0
	ds_read_b32 v1, v0 offset:4
	v_readlane_b32 s0, v251, 2
	v_readlane_b32 s6, v251, 5
	v_readlane_b32 s7, v251, 6
	s_lshl_b32 s0, s0, 8
	s_add_u32 s8, s6, s0
	s_addc_u32 s9, s7, 0
	v_mov_b32_e32 v3, 1
	v_mov_b32_e32 v4, 0x1000
	s_nop 4
	global_atomic_add v3, v4, v3, s[8:9] offset:1024 sc0
	buffer_inv sc1
	s_sub_u32 s10, 1, s66
	s_add_u32 s11, s10, 1
	s_waitcnt lgkmcnt(0)
	v_readfirstlane_b32 s12, v2
	v_readfirstlane_b32 s13, v1
	s_mul_i32 s14, s12, s11
	s_mul_i32 s15, s13, s11
	s_waitcnt vmcnt(0)
	v_readfirstlane_b32 s16, v3
	s_add_u32 s16, s16, 1
	s_cmp_lg_u32 s16, s14
	s_cbranch_scc1 .Lxb_wait_2
	buffer_wbl2 sc1
	s_waitcnt vmcnt(0)
	v_mov_b32_e32 v3, 1
	v_mov_b32_e32 v4, 0x7f000
	global_atomic_add v3, v4, v3, s[30:31] offset:1024 sc0
	s_waitcnt vmcnt(0)
	v_readfirstlane_b32 s16, v3
	s_add_u32 s16, s16, 1
	s_cmp_lg_u32 s16, s15
	s_cbranch_scc1 .Lxb_wait_2
	v_mov_b32_e32 v3, 1
	v_mov_b32_e32 v4, 0x2400
	global_atomic_add v4, v3, s[6:7]
	v_add_u32_e32 v4, 0x100, v4
	global_atomic_add v4, v3, s[6:7]
	v_add_u32_e32 v4, 0x100, v4
	global_atomic_add v4, v3, s[6:7]
	v_add_u32_e32 v4, 0x100, v4
	global_atomic_add v4, v3, s[6:7]
	v_add_u32_e32 v4, 0x100, v4
	global_atomic_add v4, v3, s[6:7]
	v_add_u32_e32 v4, 0x100, v4
	global_atomic_add v4, v3, s[6:7]
	v_add_u32_e32 v4, 0x100, v4
	global_atomic_add v4, v3, s[6:7]
	v_add_u32_e32 v4, 0x100, v4
	global_atomic_add v4, v3, s[6:7]
	v_add_u32_e32 v4, 0x100, v4
	global_atomic_add v4, v3, s[6:7]
	v_add_u32_e32 v4, 0x100, v4
	global_atomic_add v4, v3, s[6:7]
	v_add_u32_e32 v4, 0x100, v4
	global_atomic_add v4, v3, s[6:7]
	v_add_u32_e32 v4, 0x100, v4
	global_atomic_add v4, v3, s[6:7]
	v_add_u32_e32 v4, 0x100, v4
	global_atomic_add v4, v3, s[6:7]
	v_add_u32_e32 v4, 0x100, v4
	global_atomic_add v4, v3, s[6:7]
	v_add_u32_e32 v4, 0x100, v4
	global_atomic_add v4, v3, s[6:7]
	v_add_u32_e32 v4, 0x100, v4
	global_atomic_add v4, v3, s[6:7]
	v_add_u32_e32 v4, 0x100, v4
	v_mov_b32_e32 v4, 0x7f000
	global_atomic_add v4, v3, s[30:31] offset:1280

.LBB0_218:
	v_ashrrev_i32_e32 v66, 1, v102
	v_lshrrev_b32_e32 v64, 3, v102
	v_and_b32_e32 v72, 4, v64
	v_add_u32_e32 v64, s75, v66
	v_bfe_u32 v73, v64, 6, 4
	v_lshlrev_b32_e32 v64, 1, v102
	v_and_b32_e32 v74, 62, v64
	v_cndmask_b32_e64 v64, 0, 1, s[12:13]
	s_and_b64 vcc, exec, s[10:11]
	v_cmp_ne_u32_e64 s[10:11], 1, v64
	s_cbranch_vccz .LBB0_223
	s_and_b64 vcc, exec, s[10:11]
	s_cbranch_vccnz .LBB0_221
	v_lshlrev_b32_e32 v175, 2, v74
	v_mov_b32_e32 v174, v72
	v_cndmask_b32_e64 v174, v174, v73, s[8:9]
	v_lshl_or_b32 v174, v174, 8, v175
	global_load_dwordx2 v[110:111], v174, s[22:23]
	v_or_b32_e32 v174, 1, v72
	v_cndmask_b32_e64 v174, v174, v73, s[8:9]
	v_lshl_or_b32 v174, v174, 8, v175
	global_load_dwordx2 v[112:113], v174, s[22:23]
	v_or_b32_e32 v174, 2, v72
	v_cndmask_b32_e64 v174, v174, v73, s[8:9]
	v_lshl_or_b32 v174, v174, 8, v175
	global_load_dwordx2 v[114:115], v174, s[22:23]
	v_or_b32_e32 v174, 3, v72
	v_cndmask_b32_e64 v174, v174, v73, s[8:9]
	v_lshl_or_b32 v174, v174, 8, v175
	global_load_dwordx2 v[116:117], v174, s[22:23]
	v_or_b32_e32 v174, 8, v72
	v_cndmask_b32_e64 v174, v174, v73, s[8:9]
	v_lshl_or_b32 v174, v174, 8, v175
	global_load_dwordx2 v[118:119], v174, s[22:23]
	v_or_b32_e32 v174, 9, v72
	v_cndmask_b32_e64 v174, v174, v73, s[8:9]
	v_lshl_or_b32 v174, v174, 8, v175
	global_load_dwordx2 v[120:121], v174, s[22:23]
	v_or_b32_e32 v174, 10, v72
	v_cndmask_b32_e64 v174, v174, v73, s[8:9]
	v_lshl_or_b32 v174, v174, 8, v175
	global_load_dwordx2 v[122:123], v174, s[22:23]
	v_or_b32_e32 v174, 11, v72
	v_cndmask_b32_e64 v174, v174, v73, s[8:9]
	v_lshl_or_b32 v174, v174, 8, v175
	global_load_dwordx2 v[124:125], v174, s[22:23]
	v_or_b32_e32 v174, 16, v72
	v_cndmask_b32_e64 v174, v174, v73, s[8:9]
	v_lshl_or_b32 v174, v174, 8, v175
	global_load_dwordx2 v[126:127], v174, s[22:23]
	v_or_b32_e32 v174, 17, v72
	v_cndmask_b32_e64 v174, v174, v73, s[8:9]
	v_lshl_or_b32 v174, v174, 8, v175
	global_load_dwordx2 v[128:129], v174, s[22:23]
	v_or_b32_e32 v174, 18, v72
	v_cndmask_b32_e64 v174, v174, v73, s[8:9]
	v_lshl_or_b32 v174, v174, 8, v175
	global_load_dwordx2 v[130:131], v174, s[22:23]
	v_or_b32_e32 v174, 19, v72
	v_cndmask_b32_e64 v174, v174, v73, s[8:9]
	v_lshl_or_b32 v174, v174, 8, v175
	global_load_dwordx2 v[132:133], v174, s[22:23]
	v_or_b32_e32 v174, 24, v72
	v_cndmask_b32_e64 v174, v174, v73, s[8:9]
	v_lshl_or_b32 v174, v174, 8, v175
	global_load_dwordx2 v[134:135], v174, s[22:23]
	v_or_b32_e32 v174, 25, v72
	v_cndmask_b32_e64 v174, v174, v73, s[8:9]
	v_lshl_or_b32 v174, v174, 8, v175
	global_load_dwordx2 v[136:137], v174, s[22:23]
	v_or_b32_e32 v174, 26, v72
	v_cndmask_b32_e64 v174, v174, v73, s[8:9]
	v_lshl_or_b32 v174, v174, 8, v175
	global_load_dwordx2 v[138:139], v174, s[22:23]
	v_or_b32_e32 v174, 27, v72
	v_cndmask_b32_e64 v174, v174, v73, s[8:9]
	v_lshl_or_b32 v174, v174, 8, v175
	global_load_dwordx2 v[140:141], v174, s[22:23]
	v_or_b32_e32 v174, 32, v72
	v_cndmask_b32_e64 v174, v174, v73, s[8:9]
	v_lshl_or_b32 v174, v174, 8, v175
	global_load_dwordx2 v[142:143], v174, s[22:23]
	v_or_b32_e32 v174, 33, v72
	v_cndmask_b32_e64 v174, v174, v73, s[8:9]
	v_lshl_or_b32 v174, v174, 8, v175
	global_load_dwordx2 v[144:145], v174, s[22:23]
	v_or_b32_e32 v174, 34, v72
	v_cndmask_b32_e64 v174, v174, v73, s[8:9]
	v_lshl_or_b32 v174, v174, 8, v175
	global_load_dwordx2 v[146:147], v174, s[22:23]
	v_or_b32_e32 v174, 35, v72
	v_cndmask_b32_e64 v174, v174, v73, s[8:9]
	v_lshl_or_b32 v174, v174, 8, v175
	global_load_dwordx2 v[148:149], v174, s[22:23]
	v_or_b32_e32 v174, 40, v72
	v_cndmask_b32_e64 v174, v174, v73, s[8:9]
	v_lshl_or_b32 v174, v174, 8, v175
	global_load_dwordx2 v[150:151], v174, s[22:23]
	v_or_b32_e32 v174, 41, v72
	v_cndmask_b32_e64 v174, v174, v73, s[8:9]
	v_lshl_or_b32 v174, v174, 8, v175
	global_load_dwordx2 v[152:153], v174, s[22:23]
	v_or_b32_e32 v174, 42, v72
	v_cndmask_b32_e64 v174, v174, v73, s[8:9]
	v_lshl_or_b32 v174, v174, 8, v175
	global_load_dwordx2 v[154:155], v174, s[22:23]
	v_or_b32_e32 v174, 43, v72
	v_cndmask_b32_e64 v174, v174, v73, s[8:9]
	v_lshl_or_b32 v174, v174, 8, v175
	global_load_dwordx2 v[156:157], v174, s[22:23]
	v_or_b32_e32 v174, 48, v72
	v_cndmask_b32_e64 v174, v174, v73, s[8:9]
	v_lshl_or_b32 v174, v174, 8, v175
	global_load_dwordx2 v[158:159], v174, s[22:23]
	v_or_b32_e32 v174, 49, v72
	v_cndmask_b32_e64 v174, v174, v73, s[8:9]
	v_lshl_or_b32 v174, v174, 8, v175
	global_load_dwordx2 v[160:161], v174, s[22:23]
	v_or_b32_e32 v174, 50, v72
	v_cndmask_b32_e64 v174, v174, v73, s[8:9]
	v_lshl_or_b32 v174, v174, 8, v175
	global_load_dwordx2 v[162:163], v174, s[22:23]
	v_or_b32_e32 v174, 51, v72
	v_cndmask_b32_e64 v174, v174, v73, s[8:9]
	v_lshl_or_b32 v174, v174, 8, v175
	global_load_dwordx2 v[164:165], v174, s[22:23]
	v_or_b32_e32 v174, 56, v72
	v_cndmask_b32_e64 v174, v174, v73, s[8:9]
	v_lshl_or_b32 v174, v174, 8, v175
	global_load_dwordx2 v[166:167], v174, s[22:23]
	v_or_b32_e32 v174, 57, v72
	v_cndmask_b32_e64 v174, v174, v73, s[8:9]
	v_lshl_or_b32 v174, v174, 8, v175
	global_load_dwordx2 v[168:169], v174, s[22:23]
	v_or_b32_e32 v174, 58, v72
	v_cndmask_b32_e64 v174, v174, v73, s[8:9]
	v_lshl_or_b32 v174, v174, 8, v175
	global_load_dwordx2 v[170:171], v174, s[22:23]
	v_or_b32_e32 v174, 59, v72
	v_cndmask_b32_e64 v174, v174, v73, s[8:9]
	v_lshl_or_b32 v174, v174, 8, v175
	global_load_dwordx2 v[172:173], v174, s[22:23]
	s_waitcnt vmcnt(0)
	v_mov_b64_e32 v[64:65], v[110:111]
	s_waitcnt vmcnt(0)
	v_pk_mul_f32 v[70:71], v[32:33], v[64:65] op_sel:[0,1] op_sel_hi:[0,0]
	v_pk_mul_f32 v[68:69], v[48:49], v[64:65]
	v_pk_fma_f32 v[64:65], v[48:49], v[64:65], v[70:71] op_sel_hi:[0,1,1]
	v_sub_f32_e32 v64, v68, v70
	s_branch .LBB0_222

.LBB0_239:
	s_and_b64 vcc, exec, s[16:17]
	s_cbranch_vccz .LBB0_247
	s_and_b64 vcc, exec, s[10:11]
	s_cbranch_vccnz .LBB0_249
	v_mov_b64_e32 v[70:71], v[112:113]
	s_waitcnt vmcnt(0)
	v_pk_mul_f32 v[78:79], v[32:33], v[70:71] op_sel:[1,1] op_sel_hi:[1,0]
	v_pk_mul_f32 v[76:77], v[48:49], v[70:71] op_sel:[1,0]
	v_pk_fma_f32 v[70:71], v[48:49], v[70:71], v[78:79] op_sel:[1,0,0]
	s_nop 0
	v_sub_f32_e32 v70, v76, v78
	s_branch .LBB0_250

.LBB0_265:
	s_and_b64 vcc, exec, s[16:17]
	s_cbranch_vccz .LBB0_273
	s_and_b64 vcc, exec, s[10:11]
	s_cbranch_vccnz .LBB0_275
	v_mov_b64_e32 v[32:33], v[114:115]
	s_waitcnt vmcnt(0)
	v_pk_mul_f32 v[76:77], v[34:35], v[32:33] op_sel:[0,1] op_sel_hi:[0,0]
	v_pk_mul_f32 v[48:49], v[50:51], v[32:33]
	v_pk_fma_f32 v[32:33], v[50:51], v[32:33], v[76:77] op_sel_hi:[0,1,1]
	v_sub_f32_e32 v32, v48, v76
	s_branch .LBB0_276

.LBB0_291:
	s_and_b64 vcc, exec, s[16:17]
	s_cbranch_vccz .LBB0_299
	s_and_b64 vcc, exec, s[10:11]
	s_cbranch_vccnz .LBB0_301
	v_mov_b64_e32 v[48:49], v[116:117]
	v_mov_b32_e32 v50, v35
	v_mov_b32_e32 v34, v51
	s_waitcnt vmcnt(0)
	v_pk_mul_f32 v[78:79], v[50:51], v[48:49] op_sel:[0,1] op_sel_hi:[0,0]
	v_pk_mul_f32 v[76:77], v[34:35], v[48:49] op_sel_hi:[0,1]
	v_pk_fma_f32 v[48:49], v[34:35], v[48:49], v[78:79] op_sel_hi:[0,1,1]
	v_sub_f32_e32 v48, v76, v78
	s_branch .LBB0_302

.LBB0_311:
	s_and_b64 vcc, exec, s[34:35]
	s_cbranch_vccz .LBB0_327
	s_and_b64 vcc, exec, s[10:11]
	s_cbranch_vccnz .LBB0_329
	v_mov_b64_e32 v[32:33], v[118:119]
	s_waitcnt vmcnt(0)
	v_pk_mul_f32 v[48:49], v[36:37], v[32:33] op_sel:[0,1] op_sel_hi:[0,0]
	v_pk_mul_f32 v[34:35], v[52:53], v[32:33]
	v_pk_fma_f32 v[32:33], v[52:53], v[32:33], v[48:49] op_sel_hi:[0,1,1]
	v_sub_f32_e32 v32, v34, v48
	s_branch .LBB0_330

.LBB0_345:
	s_and_b64 vcc, exec, s[34:35]
	s_cbranch_vccz .LBB0_353
	s_and_b64 vcc, exec, s[10:11]
	s_cbranch_vccnz .LBB0_355
	v_mov_b64_e32 v[34:35], v[120:121]
	v_mov_b32_e32 v48, v37
	v_mov_b32_e32 v36, v53
	s_waitcnt vmcnt(0)
	v_pk_mul_f32 v[48:49], v[48:49], v[34:35] op_sel:[0,1] op_sel_hi:[0,0]
	v_pk_mul_f32 v[68:69], v[36:37], v[34:35] op_sel_hi:[0,1]
	v_pk_fma_f32 v[34:35], v[36:37], v[34:35], v[48:49] op_sel_hi:[0,1,1]
	v_sub_f32_e32 v34, v68, v48
	s_branch .LBB0_356

.LBB0_371:
	s_and_b64 vcc, exec, s[34:35]
	s_cbranch_vccz .LBB0_379
	s_and_b64 vcc, exec, s[10:11]
	s_cbranch_vccnz .LBB0_381
	v_mov_b64_e32 v[36:37], v[122:123]
	s_waitcnt vmcnt(0)
	v_pk_mul_f32 v[52:53], v[38:39], v[36:37] op_sel:[0,1] op_sel_hi:[0,0]
	v_pk_mul_f32 v[48:49], v[54:55], v[36:37]
	v_pk_fma_f32 v[36:37], v[54:55], v[36:37], v[52:53] op_sel_hi:[0,1,1]
	v_sub_f32_e32 v36, v48, v52
	s_branch .LBB0_382

.LBB0_397:
	s_and_b64 vcc, exec, s[34:35]
	s_cbranch_vccz .LBB0_405
	s_and_b64 vcc, exec, s[10:11]
	s_cbranch_vccnz .LBB0_407
	v_mov_b64_e32 v[48:49], v[124:125]
	v_mov_b32_e32 v52, v39
	v_mov_b32_e32 v38, v55
	s_waitcnt vmcnt(0)
	v_pk_mul_f32 v[52:53], v[52:53], v[48:49] op_sel:[0,1] op_sel_hi:[0,0]
	v_pk_mul_f32 v[68:69], v[38:39], v[48:49] op_sel_hi:[0,1]
	v_pk_fma_f32 v[48:49], v[38:39], v[48:49], v[52:53] op_sel_hi:[0,1,1]
	v_sub_f32_e32 v48, v68, v52
	s_branch .LBB0_408

.LBB0_415:
	s_and_b64 vcc, exec, s[34:35]
	s_cbranch_vccz .LBB0_433
	s_and_b64 vcc, exec, s[10:11]
	s_cbranch_vccnz .LBB0_435
	v_mov_b64_e32 v[32:33], v[126:127]
	s_waitcnt vmcnt(0)
	v_pk_mul_f32 v[36:37], v[40:41], v[32:33] op_sel:[0,1] op_sel_hi:[0,0]
	v_pk_mul_f32 v[34:35], v[56:57], v[32:33]
	v_pk_fma_f32 v[32:33], v[56:57], v[32:33], v[36:37] op_sel_hi:[0,1,1]
	v_sub_f32_e32 v32, v34, v36
	s_branch .LBB0_436

.LBB0_451:
	s_and_b64 vcc, exec, s[34:35]
	s_cbranch_vccz .LBB0_459
	s_and_b64 vcc, exec, s[10:11]
	s_cbranch_vccnz .LBB0_461
	v_mov_b64_e32 v[34:35], v[128:129]
	v_mov_b32_e32 v38, v41
	v_mov_b32_e32 v36, v57
	s_waitcnt vmcnt(0)
	v_pk_mul_f32 v[38:39], v[38:39], v[34:35] op_sel:[0,1] op_sel_hi:[0,0]
	v_pk_mul_f32 v[48:49], v[36:37], v[34:35] op_sel_hi:[0,1]
	v_pk_fma_f32 v[34:35], v[36:37], v[34:35], v[38:39] op_sel_hi:[0,1,1]
	v_sub_f32_e32 v34, v48, v38
	s_branch .LBB0_462

.LBB0_477:
	s_and_b64 vcc, exec, s[34:35]
	s_cbranch_vccz .LBB0_485
	s_and_b64 vcc, exec, s[10:11]
	s_cbranch_vccnz .LBB0_487
	v_mov_b64_e32 v[36:37], v[130:131]
	s_waitcnt vmcnt(0)
	v_pk_mul_f32 v[40:41], v[42:43], v[36:37] op_sel:[0,1] op_sel_hi:[0,0]
	v_pk_mul_f32 v[38:39], v[58:59], v[36:37]
	v_pk_fma_f32 v[36:37], v[58:59], v[36:37], v[40:41] op_sel_hi:[0,1,1]
	v_sub_f32_e32 v36, v38, v40
	s_branch .LBB0_488

.LBB0_503:
	s_and_b64 vcc, exec, s[34:35]
	s_cbranch_vccz .LBB0_511
	s_and_b64 vcc, exec, s[10:11]
	s_cbranch_vccnz .LBB0_513
	v_mov_b64_e32 v[38:39], v[132:133]
	v_mov_b32_e32 v42, v43
	v_mov_b32_e32 v40, v59
	s_waitcnt vmcnt(0)
	v_pk_mul_f32 v[52:53], v[42:43], v[38:39] op_sel:[0,1] op_sel_hi:[0,0]
	v_pk_mul_f32 v[48:49], v[40:41], v[38:39] op_sel_hi:[0,1]
	v_pk_fma_f32 v[38:39], v[40:41], v[38:39], v[52:53] op_sel_hi:[0,1,1]
	v_sub_f32_e32 v38, v48, v52
	s_branch .LBB0_514

.LBB0_521:
	s_and_b64 vcc, exec, s[34:35]
	s_cbranch_vccz .LBB0_539
	s_and_b64 vcc, exec, s[10:11]
	s_cbranch_vccnz .LBB0_541
	v_mov_b64_e32 v[32:33], v[134:135]
	s_waitcnt vmcnt(0)
	v_pk_mul_f32 v[36:37], v[44:45], v[32:33] op_sel:[0,1] op_sel_hi:[0,0]
	v_pk_mul_f32 v[34:35], v[60:61], v[32:33]
	v_pk_fma_f32 v[32:33], v[60:61], v[32:33], v[36:37] op_sel_hi:[0,1,1]
	v_sub_f32_e32 v32, v34, v36
	s_branch .LBB0_542

.LBB0_557:
	s_and_b64 vcc, exec, s[34:35]
	s_cbranch_vccz .LBB0_565
	s_and_b64 vcc, exec, s[10:11]
	s_cbranch_vccnz .LBB0_567
	v_mov_b64_e32 v[34:35], v[136:137]
	v_mov_b32_e32 v38, v45
	v_mov_b32_e32 v36, v61
	s_waitcnt vmcnt(0)
	v_pk_mul_f32 v[38:39], v[38:39], v[34:35] op_sel:[0,1] op_sel_hi:[0,0]
	v_pk_mul_f32 v[40:41], v[36:37], v[34:35] op_sel_hi:[0,1]
	v_pk_fma_f32 v[34:35], v[36:37], v[34:35], v[38:39] op_sel_hi:[0,1,1]
	v_sub_f32_e32 v34, v40, v38
	s_branch .LBB0_568

.LBB0_583:
	s_and_b64 vcc, exec, s[34:35]
	s_cbranch_vccz .LBB0_591
	s_and_b64 vcc, exec, s[10:11]
	s_cbranch_vccnz .LBB0_593
	v_mov_b64_e32 v[36:37], v[138:139]
	s_waitcnt vmcnt(0)
	v_pk_mul_f32 v[40:41], v[46:47], v[36:37] op_sel:[0,1] op_sel_hi:[0,0]
	v_pk_mul_f32 v[38:39], v[62:63], v[36:37]
	v_pk_fma_f32 v[36:37], v[62:63], v[36:37], v[40:41] op_sel_hi:[0,1,1]
	v_sub_f32_e32 v36, v38, v40
	s_branch .LBB0_594

.LBB0_609:
	s_and_b64 vcc, exec, s[34:35]
	s_cbranch_vccz .LBB0_617
	s_and_b64 vcc, exec, s[10:11]
	s_cbranch_vccnz .LBB0_619
	v_mov_b64_e32 v[38:39], v[140:141]
	v_mov_b32_e32 v42, v47
	v_mov_b32_e32 v40, v63
	s_waitcnt vmcnt(0)
	v_pk_mul_f32 v[42:43], v[42:43], v[38:39] op_sel:[0,1] op_sel_hi:[0,0]
	v_pk_mul_f32 v[44:45], v[40:41], v[38:39] op_sel_hi:[0,1]
	v_pk_fma_f32 v[38:39], v[40:41], v[38:39], v[42:43] op_sel_hi:[0,1,1]
	v_sub_f32_e32 v38, v44, v42
	s_branch .LBB0_620

.LBB0_627:
	s_and_b64 vcc, exec, s[34:35]
	s_cbranch_vccz .LBB0_645
	s_and_b64 vcc, exec, s[10:11]
	s_cbranch_vccnz .LBB0_647
	v_mov_b64_e32 v[32:33], v[142:143]
	s_waitcnt vmcnt(0)
	v_pk_mul_f32 v[36:37], v[0:1], v[32:33] op_sel:[0,1] op_sel_hi:[0,0]
	v_pk_mul_f32 v[34:35], v[16:17], v[32:33]
	v_pk_fma_f32 v[32:33], v[16:17], v[32:33], v[36:37] op_sel_hi:[0,1,1]
	v_sub_f32_e32 v32, v34, v36
	s_branch .LBB0_648

.LBB0_663:
	s_and_b64 vcc, exec, s[34:35]
	s_cbranch_vccz .LBB0_671
	s_and_b64 vcc, exec, s[10:11]
	s_cbranch_vccnz .LBB0_673
	v_mov_b64_e32 v[34:35], v[144:145]
	s_waitcnt vmcnt(0)
	v_pk_mul_f32 v[38:39], v[0:1], v[34:35] op_sel:[1,1] op_sel_hi:[1,0]
	v_pk_mul_f32 v[36:37], v[16:17], v[34:35] op_sel:[1,0]
	v_pk_fma_f32 v[34:35], v[16:17], v[34:35], v[38:39] op_sel:[1,0,0]
	s_nop 0
	v_sub_f32_e32 v34, v36, v38
	s_branch .LBB0_674

.LBB0_689:
	s_and_b64 vcc, exec, s[34:35]
	s_cbranch_vccz .LBB0_697
	s_and_b64 vcc, exec, s[10:11]
	s_cbranch_vccnz .LBB0_699
	v_mov_b64_e32 v[0:1], v[146:147]
	s_waitcnt vmcnt(0)
	v_pk_mul_f32 v[36:37], v[2:3], v[0:1] op_sel:[0,1] op_sel_hi:[0,0]
	v_pk_mul_f32 v[16:17], v[18:19], v[0:1]
	v_pk_fma_f32 v[0:1], v[18:19], v[0:1], v[36:37] op_sel_hi:[0,1,1]
	v_sub_f32_e32 v0, v16, v36
	s_branch .LBB0_700

.LBB0_715:
	s_and_b64 vcc, exec, s[34:35]
	s_cbranch_vccz .LBB0_723
	s_and_b64 vcc, exec, s[10:11]
	s_cbranch_vccnz .LBB0_725
	v_mov_b64_e32 v[16:17], v[148:149]
	v_mov_b32_e32 v18, v3
	v_mov_b32_e32 v2, v19
	s_waitcnt vmcnt(0)
	v_pk_mul_f32 v[38:39], v[18:19], v[16:17] op_sel:[0,1] op_sel_hi:[0,0]
	v_pk_mul_f32 v[36:37], v[2:3], v[16:17] op_sel_hi:[0,1]
	v_pk_fma_f32 v[16:17], v[2:3], v[16:17], v[38:39] op_sel_hi:[0,1,1]
	v_sub_f32_e32 v16, v36, v38
	s_branch .LBB0_726

.LBB0_733:
	s_and_b64 vcc, exec, s[34:35]
	s_cbranch_vccz .LBB0_751
	s_and_b64 vcc, exec, s[10:11]
	s_cbranch_vccnz .LBB0_753
	v_mov_b64_e32 v[0:1], v[150:151]
	s_waitcnt vmcnt(0)
	v_pk_mul_f32 v[16:17], v[4:5], v[0:1] op_sel:[0,1] op_sel_hi:[0,0]
	v_pk_mul_f32 v[2:3], v[20:21], v[0:1]
	v_pk_fma_f32 v[0:1], v[20:21], v[0:1], v[16:17] op_sel_hi:[0,1,1]
	v_sub_f32_e32 v0, v2, v16
	s_branch .LBB0_754

.LBB0_769:
	s_and_b64 vcc, exec, s[34:35]
	s_cbranch_vccz .LBB0_777
	s_and_b64 vcc, exec, s[10:11]
	s_cbranch_vccnz .LBB0_779
	v_mov_b64_e32 v[2:3], v[152:153]
	v_mov_b32_e32 v16, v5
	v_mov_b32_e32 v4, v21
	s_waitcnt vmcnt(0)
	v_pk_mul_f32 v[16:17], v[16:17], v[2:3] op_sel:[0,1] op_sel_hi:[0,0]
	v_pk_mul_f32 v[18:19], v[4:5], v[2:3] op_sel_hi:[0,1]
	v_pk_fma_f32 v[2:3], v[4:5], v[2:3], v[16:17] op_sel_hi:[0,1,1]
	v_sub_f32_e32 v2, v18, v16
	s_branch .LBB0_780

.LBB0_795:
	s_and_b64 vcc, exec, s[34:35]
	s_cbranch_vccz .LBB0_803
	s_and_b64 vcc, exec, s[10:11]
	s_cbranch_vccnz .LBB0_805
	v_mov_b64_e32 v[4:5], v[154:155]
	s_waitcnt vmcnt(0)
	v_pk_mul_f32 v[18:19], v[6:7], v[4:5] op_sel:[0,1] op_sel_hi:[0,0]
	v_pk_mul_f32 v[16:17], v[22:23], v[4:5]
	v_pk_fma_f32 v[4:5], v[22:23], v[4:5], v[18:19] op_sel_hi:[0,1,1]
	v_sub_f32_e32 v4, v16, v18
	s_branch .LBB0_806

.LBB0_821:
	s_and_b64 vcc, exec, s[34:35]
	s_cbranch_vccz .LBB0_829
	s_and_b64 vcc, exec, s[10:11]
	s_cbranch_vccnz .LBB0_831
	v_mov_b64_e32 v[16:17], v[156:157]
	v_mov_b32_e32 v18, v7
	v_mov_b32_e32 v6, v23
	s_waitcnt vmcnt(0)
	v_pk_mul_f32 v[18:19], v[18:19], v[16:17] op_sel:[0,1] op_sel_hi:[0,0]
	v_pk_mul_f32 v[20:21], v[6:7], v[16:17] op_sel_hi:[0,1]
	v_pk_fma_f32 v[16:17], v[6:7], v[16:17], v[18:19] op_sel_hi:[0,1,1]
	v_sub_f32_e32 v16, v20, v18
	s_branch .LBB0_832

.LBB0_839:
	s_and_b64 vcc, exec, s[34:35]
	s_cbranch_vccz .LBB0_857
	s_and_b64 vcc, exec, s[10:11]
	s_cbranch_vccnz .LBB0_859
	v_mov_b64_e32 v[0:1], v[158:159]
	s_waitcnt vmcnt(0)
	v_pk_mul_f32 v[4:5], v[8:9], v[0:1] op_sel:[0,1] op_sel_hi:[0,0]
	v_pk_mul_f32 v[2:3], v[24:25], v[0:1]
	v_pk_fma_f32 v[0:1], v[24:25], v[0:1], v[4:5] op_sel_hi:[0,1,1]
	v_sub_f32_e32 v0, v2, v4
	s_branch .LBB0_860

.LBB0_875:
	s_and_b64 vcc, exec, s[34:35]
	s_cbranch_vccz .LBB0_883
	s_and_b64 vcc, exec, s[10:11]
	s_cbranch_vccnz .LBB0_885
	v_mov_b64_e32 v[2:3], v[160:161]
	v_mov_b32_e32 v6, v9
	v_mov_b32_e32 v4, v25
	s_waitcnt vmcnt(0)
	v_pk_mul_f32 v[6:7], v[6:7], v[2:3] op_sel:[0,1] op_sel_hi:[0,0]
	v_pk_mul_f32 v[16:17], v[4:5], v[2:3] op_sel_hi:[0,1]
	v_pk_fma_f32 v[2:3], v[4:5], v[2:3], v[6:7] op_sel_hi:[0,1,1]
	v_sub_f32_e32 v2, v16, v6
	s_branch .LBB0_886

.LBB0_901:
	s_and_b64 vcc, exec, s[34:35]
	s_cbranch_vccz .LBB0_909
	s_and_b64 vcc, exec, s[10:11]
	s_cbranch_vccnz .LBB0_911
	v_mov_b64_e32 v[4:5], v[162:163]
	s_waitcnt vmcnt(0)
	v_pk_mul_f32 v[8:9], v[10:11], v[4:5] op_sel:[0,1] op_sel_hi:[0,0]
	v_pk_mul_f32 v[6:7], v[26:27], v[4:5]
	v_pk_fma_f32 v[4:5], v[26:27], v[4:5], v[8:9] op_sel_hi:[0,1,1]
	v_sub_f32_e32 v4, v6, v8
	s_branch .LBB0_912

.LBB0_927:
	s_and_b64 vcc, exec, s[34:35]
	s_cbranch_vccz .LBB0_935
	s_and_b64 vcc, exec, s[10:11]
	s_cbranch_vccnz .LBB0_937
	v_mov_b64_e32 v[6:7], v[164:165]
	v_mov_b32_e32 v10, v11
	v_mov_b32_e32 v8, v27
	s_waitcnt vmcnt(0)
	v_pk_mul_f32 v[18:19], v[10:11], v[6:7] op_sel:[0,1] op_sel_hi:[0,0]
	v_pk_mul_f32 v[16:17], v[8:9], v[6:7] op_sel_hi:[0,1]
	v_pk_fma_f32 v[6:7], v[8:9], v[6:7], v[18:19] op_sel_hi:[0,1,1]
	v_sub_f32_e32 v6, v16, v18
	s_branch .LBB0_938

.LBB0_945:
	s_and_b64 vcc, exec, s[34:35]
	s_cbranch_vccz .LBB0_963
	s_and_b64 vcc, exec, s[10:11]
	s_cbranch_vccnz .LBB0_965
	v_mov_b64_e32 v[0:1], v[166:167]
	s_waitcnt vmcnt(0)
	v_pk_mul_f32 v[4:5], v[12:13], v[0:1] op_sel:[0,1] op_sel_hi:[0,0]
	v_pk_mul_f32 v[2:3], v[28:29], v[0:1]
	v_pk_fma_f32 v[0:1], v[28:29], v[0:1], v[4:5] op_sel_hi:[0,1,1]
	v_sub_f32_e32 v0, v2, v4
	s_branch .LBB0_966

.LBB0_981:
	s_and_b64 vcc, exec, s[34:35]
	s_cbranch_vccz .LBB0_989
	s_and_b64 vcc, exec, s[10:11]
	s_cbranch_vccnz .LBB0_991
	v_mov_b64_e32 v[2:3], v[168:169]
	v_mov_b32_e32 v6, v13
	v_mov_b32_e32 v4, v29
	s_waitcnt vmcnt(0)
	v_pk_mul_f32 v[6:7], v[6:7], v[2:3] op_sel:[0,1] op_sel_hi:[0,0]
	v_pk_mul_f32 v[8:9], v[4:5], v[2:3] op_sel_hi:[0,1]
	v_pk_fma_f32 v[2:3], v[4:5], v[2:3], v[6:7] op_sel_hi:[0,1,1]
	v_sub_f32_e32 v2, v8, v6
	s_branch .LBB0_992

.LBB0_1007:
	s_and_b64 vcc, exec, s[34:35]
	s_cbranch_vccz .LBB0_1015
	s_and_b64 vcc, exec, s[10:11]
	s_cbranch_vccnz .LBB0_1017
	v_mov_b64_e32 v[4:5], v[170:171]
	s_waitcnt vmcnt(0)
	v_pk_mul_f32 v[8:9], v[14:15], v[4:5] op_sel:[0,1] op_sel_hi:[0,0]
	v_pk_mul_f32 v[6:7], v[30:31], v[4:5]
	v_pk_fma_f32 v[4:5], v[30:31], v[4:5], v[8:9] op_sel_hi:[0,1,1]
	v_sub_f32_e32 v4, v6, v8
	s_branch .LBB0_1018

.LBB0_1033:
	s_and_b64 vcc, exec, s[14:15]
	s_cbranch_vccz .LBB0_1041
	s_and_b64 vcc, exec, s[10:11]
	s_cbranch_vccnz .LBB0_1043
	v_mov_b64_e32 v[6:7], v[172:173]
	v_mov_b32_e32 v10, v15
	v_mov_b32_e32 v8, v31
	s_waitcnt vmcnt(0)
	v_pk_mul_f32 v[10:11], v[10:11], v[6:7] op_sel:[0,1] op_sel_hi:[0,0]
	v_pk_mul_f32 v[12:13], v[8:9], v[6:7] op_sel_hi:[0,1]
	v_pk_fma_f32 v[6:7], v[8:9], v[6:7], v[10:11] op_sel_hi:[0,1,1]
	v_sub_f32_e32 v6, v12, v10
	s_branch .LBB0_1044

.LBB0_1554:
	s_or_b32 s46, s5, s4
	v_cndmask_b32_e64 v100, v98, v99, s[0:1]
	s_lshl_b64 s[6:7], s[46:47], 15
	v_lshl_add_u64 v[96:97], v[50:51], 0, s[6:7]
	v_pk_mul_f32 v[14:15], v[100:101], v[52:53] op_sel_hi:[0,1]
	v_pk_mul_f32 v[16:17], v[100:101], v[38:39] op_sel_hi:[0,1]
	v_cvt_pk_bf16_f32 v14, v14, v15
	v_cvt_pk_bf16_f32 v15, v16, v17
	v_pk_mul_f32 v[16:17], v[100:101], v[54:55] op_sel_hi:[0,1]
	v_pk_mul_f32 v[18:19], v[100:101], v[40:41] op_sel_hi:[0,1]
	v_lshl_add_u64 v[94:95], v[96:97], 0, v[4:5]
	v_cvt_pk_bf16_f32 v16, v16, v17
	v_cvt_pk_bf16_f32 v17, v18, v19
	global_load_dwordx4 v[144:147], v[94:95], off
	v_lshl_add_u64 v[178:179], v[96:97], 0, v[56:57]
	global_load_dwordx4 v[148:151], v[178:179], off
	v_lshl_add_u64 v[180:181], v[96:97], 0, v[60:61]
	global_load_dwordx4 v[152:155], v[180:181], off
	v_lshl_add_u64 v[182:183], v[96:97], 0, v[58:59]
	global_load_dwordx4 v[156:159], v[182:183], off
	v_lshl_add_u64 v[184:185], v[96:97], 0, v[62:63]
	global_load_dwordx4 v[160:163], v[184:185], off
	v_lshl_add_u64 v[186:187], v[96:97], 0, v[66:67]
	global_load_dwordx4 v[164:167], v[186:187], off
	v_lshl_add_u64 v[188:189], v[96:97], 0, v[64:65]
	global_load_dwordx4 v[168:171], v[188:189], off
	v_lshl_add_u64 v[190:191], v[96:97], 0, v[68:69]
	global_load_dwordx4 v[172:175], v[190:191], off
	s_mov_b64 s[6:7], 0xc0
	s_mov_b32 s5, 4
	s_and_b64 vcc, exec, s[0:1]
	s_mov_b64 s[0:1], 0
	s_waitcnt vmcnt(7)
	v_mfma_f32_16x16x32_bf16 v[6:9], v[144:147], v[14:17], v[6:9]
	s_nop 0
	s_waitcnt vmcnt(6)
	v_mfma_f32_16x16x32_bf16 v[10:13], v[148:151], v[14:17], v[10:13]
	s_waitcnt vmcnt(5)
	v_mfma_f32_16x16x32_bf16 v[26:29], v[152:155], v[14:17], v[26:29]
	s_waitcnt vmcnt(4)
	v_mfma_f32_16x16x32_bf16 v[18:21], v[156:159], v[14:17], v[34:37]
	s_nop 2
	s_waitcnt vmcnt(3)
	v_mfma_f32_16x16x32_bf16 v[22:25], v[160:163], v[14:17], v[22:25]
	s_waitcnt vmcnt(2)
	v_mfma_f32_16x16x32_bf16 v[34:37], v[164:167], v[14:17], v[42:45]
	s_nop 2
	s_waitcnt vmcnt(1)
	v_mfma_f32_16x16x32_bf16 v[30:33], v[168:171], v[14:17], v[46:49]
	s_nop 2
	v_lshl_add_u64 v[46:47], v[96:97], 0, 64
	s_waitcnt vmcnt(0)
	v_mfma_f32_16x16x32_bf16 v[0:3], v[172:175], v[14:17], v[0:3]
	v_mul_f32_e64 v14, v100, v70
	v_mul_f32_e64 v15, v100, v71
	v_pk_mul_f32 v[16:17], v[100:101], v[72:73] op_sel_hi:[0,1]
	v_cvt_pk_bf16_f32 v14, v14, v15
	v_cvt_pk_bf16_f32 v15, v16, v17
	v_pk_mul_f32 v[16:17], v[100:101], v[74:75] op_sel_hi:[0,1]
	v_pk_mul_f32 v[42:43], v[100:101], v[76:77] op_sel_hi:[0,1]
	v_cvt_pk_bf16_f32 v16, v16, v17
	v_cvt_pk_bf16_f32 v17, v42, v43
	global_load_dwordx4 v[144:147], v[94:95], off offset:64
	v_lshl_add_u64 v[178:179], v[46:47], 0, v[56:57]
	global_load_dwordx4 v[148:151], v[178:179], off
	v_lshl_add_u64 v[180:181], v[46:47], 0, v[58:59]
	global_load_dwordx4 v[152:155], v[180:181], off
	v_lshl_add_u64 v[182:183], v[46:47], 0, v[60:61]
	global_load_dwordx4 v[156:159], v[182:183], off
	v_lshl_add_u64 v[184:185], v[46:47], 0, v[62:63]
	global_load_dwordx4 v[160:163], v[184:185], off
	v_lshl_add_u64 v[186:187], v[46:47], 0, v[64:65]
	global_load_dwordx4 v[164:167], v[186:187], off
	v_lshl_add_u64 v[188:189], v[46:47], 0, v[66:67]
	global_load_dwordx4 v[168:171], v[188:189], off
	v_lshl_add_u64 v[190:191], v[46:47], 0, v[68:69]
	global_load_dwordx4 v[172:175], v[190:191], off
	s_waitcnt vmcnt(7)
	v_mfma_f32_16x16x32_bf16 v[6:9], v[144:147], v[14:17], v[6:9]
	s_waitcnt vmcnt(6)
	v_mfma_f32_16x16x32_bf16 v[10:13], v[148:151], v[14:17], v[10:13]
	s_waitcnt vmcnt(5)
	v_mfma_f32_16x16x32_bf16 v[18:21], v[152:155], v[14:17], v[18:21]
	s_waitcnt vmcnt(4)
	v_mfma_f32_16x16x32_bf16 v[26:29], v[156:159], v[14:17], v[26:29]
	s_waitcnt vmcnt(3)
	v_mfma_f32_16x16x32_bf16 v[22:25], v[160:163], v[14:17], v[22:25]
	s_waitcnt vmcnt(2)
	v_mfma_f32_16x16x32_bf16 v[30:33], v[164:167], v[14:17], v[30:33]
	s_waitcnt vmcnt(1)
	v_mfma_f32_16x16x32_bf16 v[42:45], v[168:171], v[14:17], v[34:37]
	s_nop 2
	v_lshl_add_u64 v[46:47], v[96:97], 0, s[44:45]
	v_lshl_add_u64 v[96:97], v[96:97], 0, s[6:7]
	s_waitcnt vmcnt(0)
	v_mfma_f32_16x16x32_bf16 v[0:3], v[172:175], v[14:17], v[0:3]
	v_mul_f32_e64 v14, v100, v78
	v_mul_f32_e64 v15, v100, v79
	v_pk_mul_f32 v[16:17], v[100:101], v[80:81] op_sel_hi:[0,1]
	v_cvt_pk_bf16_f32 v14, v14, v15
	v_cvt_pk_bf16_f32 v15, v16, v17
	v_pk_mul_f32 v[16:17], v[100:101], v[82:83] op_sel_hi:[0,1]
	v_pk_mul_f32 v[34:35], v[100:101], v[84:85] op_sel_hi:[0,1]
	v_cvt_pk_bf16_f32 v16, v16, v17
	v_cvt_pk_bf16_f32 v17, v34, v35
	global_load_dwordx4 v[144:147], v[94:95], off offset:128
	v_lshl_add_u64 v[178:179], v[46:47], 0, v[56:57]
	global_load_dwordx4 v[148:151], v[178:179], off
	v_lshl_add_u64 v[180:181], v[46:47], 0, v[58:59]
	global_load_dwordx4 v[152:155], v[180:181], off
	v_lshl_add_u64 v[182:183], v[46:47], 0, v[60:61]
	global_load_dwordx4 v[156:159], v[182:183], off
	v_lshl_add_u64 v[184:185], v[46:47], 0, v[62:63]
	global_load_dwordx4 v[160:163], v[184:185], off
	v_lshl_add_u64 v[186:187], v[46:47], 0, v[64:65]
	global_load_dwordx4 v[164:167], v[186:187], off
	v_lshl_add_u64 v[188:189], v[46:47], 0, v[66:67]
	global_load_dwordx4 v[168:171], v[188:189], off
	v_lshl_add_u64 v[190:191], v[46:47], 0, v[68:69]
	global_load_dwordx4 v[172:175], v[190:191], off
	s_waitcnt vmcnt(7)
	v_mfma_f32_16x16x32_bf16 v[6:9], v[144:147], v[14:17], v[6:9]
	s_waitcnt vmcnt(6)
	v_mfma_f32_16x16x32_bf16 v[10:13], v[148:151], v[14:17], v[10:13]
	s_waitcnt vmcnt(5)
	v_mfma_f32_16x16x32_bf16 v[34:37], v[152:155], v[14:17], v[18:21]
	s_nop 2
	s_waitcnt vmcnt(4)
	v_mfma_f32_16x16x32_bf16 v[26:29], v[156:159], v[14:17], v[26:29]
	s_waitcnt vmcnt(3)
	v_mfma_f32_16x16x32_bf16 v[22:25], v[160:163], v[14:17], v[22:25]
	s_waitcnt vmcnt(2)
	v_mfma_f32_16x16x32_bf16 v[30:33], v[164:167], v[14:17], v[30:33]
	s_waitcnt vmcnt(1)
	v_mfma_f32_16x16x32_bf16 v[18:21], v[168:171], v[14:17], v[42:45]
	s_nop 2
	s_waitcnt vmcnt(0)
	v_mfma_f32_16x16x32_bf16 v[0:3], v[172:175], v[14:17], v[0:3]
	v_mul_f32_e64 v14, v100, v86
	v_mul_f32_e64 v15, v100, v87
	v_pk_mul_f32 v[16:17], v[100:101], v[88:89] op_sel_hi:[0,1]
	v_cvt_pk_bf16_f32 v14, v14, v15
	v_cvt_pk_bf16_f32 v15, v16, v17
	v_pk_mul_f32 v[16:17], v[100:101], v[90:91] op_sel_hi:[0,1]
	v_pk_mul_f32 v[42:43], v[100:101], v[92:93] op_sel_hi:[0,1]
	v_cvt_pk_bf16_f32 v16, v16, v17
	v_cvt_pk_bf16_f32 v17, v42, v43
	global_load_dwordx4 v[144:147], v[94:95], off offset:192
	v_lshl_add_u64 v[178:179], v[96:97], 0, v[56:57]
	global_load_dwordx4 v[148:151], v[178:179], off
	v_lshl_add_u64 v[180:181], v[96:97], 0, v[58:59]
	global_load_dwordx4 v[152:155], v[180:181], off
	v_lshl_add_u64 v[182:183], v[96:97], 0, v[60:61]
	global_load_dwordx4 v[156:159], v[182:183], off
	v_lshl_add_u64 v[184:185], v[96:97], 0, v[62:63]
	global_load_dwordx4 v[160:163], v[184:185], off
	v_lshl_add_u64 v[186:187], v[96:97], 0, v[64:65]
	global_load_dwordx4 v[164:167], v[186:187], off
	v_lshl_add_u64 v[188:189], v[96:97], 0, v[66:67]
	global_load_dwordx4 v[168:171], v[188:189], off
	v_lshl_add_u64 v[190:191], v[96:97], 0, v[68:69]
	global_load_dwordx4 v[172:175], v[190:191], off
	s_waitcnt vmcnt(7)
	v_mfma_f32_16x16x32_bf16 v[6:9], v[144:147], v[14:17], v[6:9]
	s_waitcnt vmcnt(6)
	v_mfma_f32_16x16x32_bf16 v[10:13], v[148:151], v[14:17], v[10:13]
	s_waitcnt vmcnt(5)
	v_mfma_f32_16x16x32_bf16 v[34:37], v[152:155], v[14:17], v[34:37]
	s_waitcnt vmcnt(4)
	v_mfma_f32_16x16x32_bf16 v[26:29], v[156:159], v[14:17], v[26:29]
	s_waitcnt vmcnt(3)
	v_mfma_f32_16x16x32_bf16 v[22:25], v[160:163], v[14:17], v[22:25]
	s_waitcnt vmcnt(2)
	v_mfma_f32_16x16x32_bf16 v[46:49], v[164:167], v[14:17], v[30:33]
	s_nop 2
	s_waitcnt vmcnt(1)
	v_mfma_f32_16x16x32_bf16 v[42:45], v[168:171], v[14:17], v[18:21]
	s_nop 2
	s_waitcnt vmcnt(0)
	v_mfma_f32_16x16x32_bf16 v[0:3], v[172:175], v[14:17], v[0:3]
	s_cbranch_vccnz .LBB0_1554
	v_mov_b32_e32 v14, v6
	v_mov_b32_e32 v15, v10
	v_mov_b32_e32 v16, v7
	v_mov_b32_e32 v17, v11
	v_pk_add_f32 v[14:15], v[14:15], v[16:17]
	v_mov_b32_e32 v16, v8
	v_mov_b32_e32 v17, v12
	v_pk_add_f32 v[14:15], v[16:17], v[14:15]
	v_mov_b32_e32 v16, v9
	v_mov_b32_e32 v17, v13
	v_pk_add_f32 v[14:15], v[16:17], v[14:15]
	v_mov_b32_e32 v16, v35
	v_add_f32_e32 v4, 0, v14
	v_add_f32_e32 v4, v4, v15
	v_mov_b32_e32 v14, v34
	v_mov_b32_e32 v15, v26
	v_mov_b32_e32 v17, v27
	v_pk_add_f32 v[14:15], v[14:15], v[16:17]
	v_mov_b32_e32 v16, v36
	v_mov_b32_e32 v17, v28
	v_pk_add_f32 v[14:15], v[16:17], v[14:15]
	v_mov_b32_e32 v16, v37
	v_mov_b32_e32 v17, v29
	v_pk_add_f32 v[14:15], v[16:17], v[14:15]
	v_mov_b32_e32 v16, v23
	v_add_f32_e32 v4, v4, v14
	v_add_f32_e32 v4, v4, v15
	v_mov_b32_e32 v14, v22
	v_mov_b32_e32 v15, v46
	v_mov_b32_e32 v17, v47
	v_pk_add_f32 v[14:15], v[14:15], v[16:17]
	v_mov_b32_e32 v16, v24
	v_mov_b32_e32 v17, v48
	v_pk_add_f32 v[14:15], v[16:17], v[14:15]
	v_mov_b32_e32 v16, v25
	v_mov_b32_e32 v17, v49
	v_pk_add_f32 v[14:15], v[16:17], v[14:15]
	v_mov_b32_e32 v16, v43
	v_add_f32_e32 v4, v4, v14
	v_add_f32_e32 v4, v4, v15
	v_mov_b32_e32 v14, v42
	v_mov_b32_e32 v15, v0
	v_mov_b32_e32 v17, v1
	v_pk_add_f32 v[14:15], v[14:15], v[16:17]
	v_mov_b32_e32 v16, v44
	v_mov_b32_e32 v17, v2
	v_pk_add_f32 v[14:15], v[16:17], v[14:15]
	v_mov_b32_e32 v16, v45
	v_mov_b32_e32 v17, v3
	v_pk_add_f32 v[14:15], v[16:17], v[14:15]
	v_or3_b32 v110, v141, s2, v110
	v_add_f32_e32 v4, v4, v14
	v_add_f32_e32 v4, v4, v15
	v_and_b32_e32 v15, 64, v238
	v_xor_b32_e32 v14, 16, v238
	v_add_u32_e32 v20, 64, v15
	v_cmp_lt_i32_e32 vcc, v14, v20
	v_lshlrev_b64 v[16:17], 1, v[110:111]
	s_mov_b32 s0, 0x800000
	v_cndmask_b32_e32 v14, v238, v14, vcc
	v_lshlrev_b32_e32 v70, 2, v14
	v_lshl_add_u64 v[14:15], s[50:51], 0, v[16:17]
	global_load_dwordx2 v[18:19], v[14:15], off
	ds_bpermute_b32 v21, v70, v4
	v_xor_b32_e32 v14, 32, v238
	v_cmp_lt_i32_e32 vcc, v14, v20
	v_lshl_add_u64 v[16:17], s[52:53], 0, v[16:17]
	s_waitcnt lgkmcnt(0)
	v_add_f32_e32 v4, v4, v21
	v_cndmask_b32_e32 v14, v238, v14, vcc
	v_lshlrev_b32_e32 v71, 2, v14
	ds_bpermute_b32 v14, v71, v4
	s_waitcnt lgkmcnt(0)
	v_add_f32_e32 v4, v4, v14
	v_mul_f32_e32 v4, 0x3c000000, v4
	v_pk_add_f32 v[6:7], v[6:7], v[4:5] op_sel_hi:[1,0] neg_lo:[0,1] neg_hi:[0,1]
	v_pk_add_f32 v[8:9], v[8:9], v[4:5] op_sel_hi:[1,0] neg_lo:[0,1] neg_hi:[0,1]
	v_pk_mul_f32 v[32:33], v[6:7], v[6:7]
	v_pk_add_f32 v[14:15], v[0:1], v[4:5] op_sel_hi:[1,0] neg_lo:[0,1] neg_hi:[0,1]
	v_pk_add_f32 v[0:1], v[2:3], v[4:5] op_sel_hi:[1,0] neg_lo:[0,1] neg_hi:[0,1]
	v_pk_mul_f32 v[30:31], v[8:9], v[8:9]
	v_pk_add_f32 v[12:13], v[12:13], v[4:5] op_sel_hi:[1,0] neg_lo:[0,1] neg_hi:[0,1]
	v_pk_add_f32 v[10:11], v[10:11], v[4:5] op_sel_hi:[1,0] neg_lo:[0,1] neg_hi:[0,1]
	v_pk_add_f32 v[36:37], v[36:37], v[4:5] op_sel_hi:[1,0] neg_lo:[0,1] neg_hi:[0,1]
	v_pk_add_f32 v[34:35], v[34:35], v[4:5] op_sel_hi:[1,0] neg_lo:[0,1] neg_hi:[0,1]
	v_pk_add_f32 v[28:29], v[28:29], v[4:5] op_sel_hi:[1,0] neg_lo:[0,1] neg_hi:[0,1]
	v_pk_add_f32 v[26:27], v[26:27], v[4:5] op_sel_hi:[1,0] neg_lo:[0,1] neg_hi:[0,1]
	v_pk_add_f32 v[24:25], v[24:25], v[4:5] op_sel_hi:[1,0] neg_lo:[0,1] neg_hi:[0,1]
	v_pk_add_f32 v[22:23], v[22:23], v[4:5] op_sel_hi:[1,0] neg_lo:[0,1] neg_hi:[0,1]
	v_pk_add_f32 v[48:49], v[48:49], v[4:5] op_sel_hi:[1,0] neg_lo:[0,1] neg_hi:[0,1]
	v_pk_add_f32 v[46:47], v[46:47], v[4:5] op_sel_hi:[1,0] neg_lo:[0,1] neg_hi:[0,1]
	v_pk_add_f32 v[44:45], v[44:45], v[4:5] op_sel_hi:[1,0] neg_lo:[0,1] neg_hi:[0,1]
	v_pk_add_f32 v[42:43], v[42:43], v[4:5] op_sel_hi:[1,0] neg_lo:[0,1] neg_hi:[0,1]
	v_add_f32_e32 v4, v32, v33
	v_add_f32_e32 v4, v30, v4
	v_pk_mul_f32 v[40:41], v[10:11], v[10:11]
	v_add_f32_e32 v4, v31, v4
	v_add_f32_e32 v4, v40, v4
	v_pk_mul_f32 v[38:39], v[12:13], v[12:13]
	v_add_f32_e32 v4, v41, v4
	v_add_f32_e32 v4, v38, v4
	v_pk_mul_f32 v[52:53], v[34:35], v[34:35]
	v_add_f32_e32 v4, v39, v4
	v_add_f32_e32 v4, v52, v4
	v_pk_mul_f32 v[50:51], v[36:37], v[36:37]
	v_add_f32_e32 v4, v53, v4
	v_add_f32_e32 v4, v50, v4
	v_pk_mul_f32 v[56:57], v[26:27], v[26:27]
	v_add_f32_e32 v4, v51, v4
	v_add_f32_e32 v4, v56, v4
	v_pk_mul_f32 v[54:55], v[28:29], v[28:29]
	v_add_f32_e32 v4, v57, v4
	v_add_f32_e32 v4, v54, v4
	v_pk_mul_f32 v[60:61], v[22:23], v[22:23]
	v_add_f32_e32 v4, v55, v4
	v_add_f32_e32 v4, v60, v4
	v_pk_mul_f32 v[58:59], v[24:25], v[24:25]
	v_add_f32_e32 v4, v61, v4
	v_add_f32_e32 v4, v58, v4
	v_pk_mul_f32 v[64:65], v[46:47], v[46:47]
	v_add_f32_e32 v4, v59, v4
	v_add_f32_e32 v4, v64, v4
	v_pk_mul_f32 v[62:63], v[48:49], v[48:49]
	v_add_f32_e32 v4, v65, v4
	v_add_f32_e32 v4, v62, v4
	v_pk_mul_f32 v[68:69], v[42:43], v[42:43]
	v_add_f32_e32 v4, v63, v4
	v_add_f32_e32 v4, v68, v4
	v_pk_mul_f32 v[66:67], v[44:45], v[44:45]
	v_add_f32_e32 v4, v69, v4
	v_add_f32_e32 v4, v66, v4
	v_pk_mul_f32 v[20:21], v[14:15], v[14:15]
	v_add_f32_e32 v4, v67, v4
	v_add_f32_e32 v4, v20, v4
	v_pk_mul_f32 v[2:3], v[0:1], v[0:1]
	v_add_f32_e32 v4, v21, v4
	v_add_f32_e32 v2, v2, v4
	v_add_f32_e32 v4, v3, v2
	ds_bpermute_b32 v20, v70, v4
	s_waitcnt vmcnt(0)
	v_lshlrev_b32_e32 v2, 16, v18
	v_and_b32_e32 v3, 0xffff0000, v18
	v_lshlrev_b32_e32 v18, 16, v19
	v_and_b32_e32 v19, 0xffff0000, v19
	s_waitcnt lgkmcnt(0)
	v_add_f32_e32 v4, v4, v20
	ds_bpermute_b32 v21, v71, v4
	v_or_b32_e32 v20, 16, v110
	s_waitcnt lgkmcnt(0)
	v_add_f32_e32 v4, v4, v21
	v_fmamk_f32 v4, v4, 0x3c000000, v236
	v_mul_f32_e32 v21, 0x4b800000, v4
	v_cmp_gt_f32_e32 vcc, s0, v4
	s_nop 1
	v_cndmask_b32_e32 v4, v4, v21, vcc
	v_rsq_f32_e32 v4, v4
	v_mov_b32_e32 v21, v111
	v_lshlrev_b64 v[20:21], 1, v[20:21]
	v_lshl_add_u64 v[30:31], s[50:51], 0, v[20:21]
	v_mul_f32_e32 v32, 0x45800000, v4
	v_cndmask_b32_e32 v4, v4, v32, vcc
	v_pk_mul_f32 v[6:7], v[6:7], v[4:5] op_sel_hi:[1,0]
	v_pk_mul_f32 v[10:11], v[10:11], v[4:5] op_sel_hi:[1,0]
	v_pk_mul_f32 v[2:3], v[6:7], v[2:3]
	v_pk_mul_f32 v[6:7], v[8:9], v[4:5] op_sel_hi:[1,0]
	v_cvt_pk_bf16_f32 v2, v2, v3
	v_pk_mul_f32 v[6:7], v[6:7], v[18:19]
	v_pk_mul_f32 v[12:13], v[12:13], v[4:5] op_sel_hi:[1,0]
	v_cvt_pk_bf16_f32 v3, v6, v7
	global_store_dwordx2 v[16:17], v[2:3], off
	global_load_dwordx2 v[2:3], v[30:31], off
	v_mov_b32_e32 v7, v111
	v_or_b32_e32 v6, 32, v110
	v_lshlrev_b64 v[6:7], 1, v[6:7]
	v_lshl_add_u64 v[8:9], s[52:53], 0, v[20:21]
	v_lshl_add_u64 v[16:17], s[50:51], 0, v[6:7]
	v_lshl_add_u64 v[6:7], s[52:53], 0, v[6:7]
	v_pk_mul_f32 v[0:1], v[0:1], v[4:5] op_sel_hi:[1,0]
	s_waitcnt vmcnt(0)
	v_lshlrev_b32_e32 v18, 16, v2
	v_and_b32_e32 v19, 0xffff0000, v2
	v_lshlrev_b32_e32 v2, 16, v3
	v_and_b32_e32 v3, 0xffff0000, v3
	v_pk_mul_f32 v[10:11], v[10:11], v[18:19]
	v_pk_mul_f32 v[2:3], v[12:13], v[2:3]
	v_cvt_pk_bf16_f32 v10, v10, v11
	v_cvt_pk_bf16_f32 v11, v2, v3
	global_store_dwordx2 v[8:9], v[10:11], off
	global_load_dwordx2 v[2:3], v[16:17], off
	v_pk_mul_f32 v[12:13], v[34:35], v[4:5] op_sel_hi:[1,0]
	v_pk_mul_f32 v[16:17], v[36:37], v[4:5] op_sel_hi:[1,0]
	v_mov_b32_e32 v9, v111
	v_or_b32_e32 v8, 48, v110
	v_lshlrev_b64 v[8:9], 1, v[8:9]
	v_lshl_add_u64 v[10:11], s[50:51], 0, v[8:9]
	v_lshl_add_u64 v[8:9], s[52:53], 0, v[8:9]
	s_waitcnt vmcnt(0)
	v_lshlrev_b32_e32 v18, 16, v2
	v_and_b32_e32 v19, 0xffff0000, v2
	v_lshlrev_b32_e32 v2, 16, v3
	v_and_b32_e32 v3, 0xffff0000, v3
	v_pk_mul_f32 v[12:13], v[12:13], v[18:19]
	v_pk_mul_f32 v[2:3], v[16:17], v[2:3]
	v_cvt_pk_bf16_f32 v12, v12, v13
	v_cvt_pk_bf16_f32 v13, v2, v3
	global_store_dwordx2 v[6:7], v[12:13], off
	global_load_dwordx2 v[2:3], v[10:11], off
	v_pk_mul_f32 v[12:13], v[26:27], v[4:5] op_sel_hi:[1,0]
	v_pk_mul_f32 v[16:17], v[28:29], v[4:5] op_sel_hi:[1,0]
	v_mov_b32_e32 v7, v111
	v_or_b32_e32 v6, 64, v110
	v_lshlrev_b64 v[6:7], 1, v[6:7]
	v_lshl_add_u64 v[10:11], s[50:51], 0, v[6:7]
	v_lshl_add_u64 v[6:7], s[52:53], 0, v[6:7]
	s_waitcnt vmcnt(0)
	v_lshlrev_b32_e32 v18, 16, v2
	v_and_b32_e32 v19, 0xffff0000, v2
	v_lshlrev_b32_e32 v2, 16, v3
	v_and_b32_e32 v3, 0xffff0000, v3
	v_pk_mul_f32 v[12:13], v[12:13], v[18:19]
	v_pk_mul_f32 v[2:3], v[16:17], v[2:3]
	v_cvt_pk_bf16_f32 v12, v12, v13
	v_cvt_pk_bf16_f32 v13, v2, v3
	global_store_dwordx2 v[8:9], v[12:13], off
	global_load_dwordx2 v[2:3], v[10:11], off
	v_pk_mul_f32 v[12:13], v[22:23], v[4:5] op_sel_hi:[1,0]
	v_pk_mul_f32 v[16:17], v[24:25], v[4:5] op_sel_hi:[1,0]
	v_mov_b32_e32 v9, v111
	v_or_b32_e32 v8, 0x50, v110
	v_lshlrev_b64 v[8:9], 1, v[8:9]
	v_lshl_add_u64 v[10:11], s[50:51], 0, v[8:9]
	v_lshl_add_u64 v[8:9], s[52:53], 0, v[8:9]
	s_waitcnt vmcnt(0)
	v_lshlrev_b32_e32 v18, 16, v2
	v_and_b32_e32 v19, 0xffff0000, v2
	v_lshlrev_b32_e32 v2, 16, v3
	v_and_b32_e32 v3, 0xffff0000, v3
	v_pk_mul_f32 v[12:13], v[12:13], v[18:19]
	v_pk_mul_f32 v[2:3], v[16:17], v[2:3]
	v_cvt_pk_bf16_f32 v12, v12, v13
	v_cvt_pk_bf16_f32 v13, v2, v3
	global_store_dwordx2 v[6:7], v[12:13], off
	global_load_dwordx2 v[2:3], v[10:11], off
	v_pk_mul_f32 v[12:13], v[46:47], v[4:5] op_sel_hi:[1,0]
	v_pk_mul_f32 v[16:17], v[48:49], v[4:5] op_sel_hi:[1,0]
	v_mov_b32_e32 v7, v111
	v_or_b32_e32 v6, 0x60, v110
	v_lshlrev_b64 v[6:7], 1, v[6:7]
	v_lshl_add_u64 v[10:11], s[50:51], 0, v[6:7]
	v_or_b32_e32 v110, 0x70, v110
	v_lshl_add_u64 v[6:7], s[52:53], 0, v[6:7]
	s_waitcnt vmcnt(0)
	v_lshlrev_b32_e32 v18, 16, v2
	v_and_b32_e32 v19, 0xffff0000, v2
	v_lshlrev_b32_e32 v2, 16, v3
	v_and_b32_e32 v3, 0xffff0000, v3
	v_pk_mul_f32 v[12:13], v[12:13], v[18:19]
	v_pk_mul_f32 v[2:3], v[16:17], v[2:3]
	v_cvt_pk_bf16_f32 v12, v12, v13
	v_cvt_pk_bf16_f32 v13, v2, v3
	global_store_dwordx2 v[8:9], v[12:13], off
	global_load_dwordx2 v[2:3], v[10:11], off
	v_pk_mul_f32 v[12:13], v[42:43], v[4:5] op_sel_hi:[1,0]
	v_pk_mul_f32 v[16:17], v[44:45], v[4:5] op_sel_hi:[1,0]
	v_lshlrev_b64 v[8:9], 1, v[110:111]
	v_lshl_add_u64 v[10:11], s[50:51], 0, v[8:9]
	s_waitcnt vmcnt(0)
	v_lshlrev_b32_e32 v18, 16, v2
	v_and_b32_e32 v19, 0xffff0000, v2
	v_lshlrev_b32_e32 v2, 16, v3
	v_and_b32_e32 v3, 0xffff0000, v3
	v_pk_mul_f32 v[12:13], v[12:13], v[18:19]
	v_pk_mul_f32 v[2:3], v[16:17], v[2:3]
	v_cvt_pk_bf16_f32 v12, v12, v13
	v_cvt_pk_bf16_f32 v13, v2, v3
	global_store_dwordx2 v[6:7], v[12:13], off
	global_load_dwordx2 v[2:3], v[10:11], off
	v_pk_mul_f32 v[6:7], v[14:15], v[4:5] op_sel_hi:[1,0]
	s_waitcnt vmcnt(0)
	v_lshlrev_b32_e32 v10, 16, v2
	v_and_b32_e32 v11, 0xffff0000, v2
	v_lshlrev_b32_e32 v2, 16, v3
	v_and_b32_e32 v3, 0xffff0000, v3
	v_pk_mul_f32 v[6:7], v[6:7], v[10:11]
	v_pk_mul_f32 v[0:1], v[0:1], v[2:3]
	v_cvt_pk_bf16_f32 v2, v6, v7
	v_cvt_pk_bf16_f32 v3, v0, v1
	v_lshl_add_u64 v[0:1], s[52:53], 0, v[8:9]
	global_store_dwordx2 v[0:1], v[2:3], off

.LBB0_1882:
	s_cmp_gt_u32 s67, 8
	s_cbranch_scc0 .LBB0_1932
	s_waitcnt vmcnt(0)
	s_waitcnt vmcnt(63) expcnt(7) lgkmcnt(15)
	s_barrier
	s_mov_b64 s[4:5], exec
	v_readlane_b32 s2, v251, 3
	v_readlane_b32 s3, v251, 4
	s_and_b64 s[2:3], s[4:5], s[2:3]
	s_mov_b64 exec, s[2:3]
	s_cbranch_execz .Lxb_done_8
	v_mov_b32_e32 v0, 0
	s_waitcnt vmcnt(0) expcnt(0) lgkmcnt(0)
	ds_read_b32 v2, v0
	ds_read_b32 v1, v0 offset:4
	v_readlane_b32 s0, v251, 2
	v_readlane_b32 s6, v251, 5
	v_readlane_b32 s7, v251, 6
	s_lshl_b32 s0, s0, 8
	s_add_u32 s8, s6, s0
	s_addc_u32 s9, s7, 0
	v_mov_b32_e32 v3, 1
	v_mov_b32_e32 v4, 0x1000
	s_nop 4
	global_atomic_add v3, v4, v3, s[8:9] offset:1024 sc0
	buffer_inv sc1
	s_sub_u32 s10, 7, s66
	s_add_u32 s11, s10, 1
	s_waitcnt lgkmcnt(0)
	v_readfirstlane_b32 s12, v2
	v_readfirstlane_b32 s13, v1
	s_mul_i32 s14, s12, s11
	s_mul_i32 s15, s13, s11
	s_waitcnt vmcnt(0)
	v_readfirstlane_b32 s16, v3
	s_add_u32 s16, s16, 1
	s_cmp_lg_u32 s16, s14
	s_cbranch_scc1 .Lxb_wait_8
	buffer_wbl2 sc1
	s_waitcnt vmcnt(0)
	v_mov_b32_e32 v3, 1
	v_mov_b32_e32 v4, 0x7f000
	global_atomic_add v3, v4, v3, s[30:31] offset:1024 sc0
	s_waitcnt vmcnt(0)
	v_readfirstlane_b32 s16, v3
	s_add_u32 s16, s16, 1
	s_cmp_lg_u32 s16, s15
	s_cbranch_scc1 .Lxb_wait_8
	v_mov_b32_e32 v3, 1
	v_mov_b32_e32 v4, 0x2400
	global_atomic_add v4, v3, s[6:7]
	v_add_u32_e32 v4, 0x100, v4
	global_atomic_add v4, v3, s[6:7]
	v_add_u32_e32 v4, 0x100, v4
	global_atomic_add v4, v3, s[6:7]
	v_add_u32_e32 v4, 0x100, v4
	global_atomic_add v4, v3, s[6:7]
	v_add_u32_e32 v4, 0x100, v4
	global_atomic_add v4, v3, s[6:7]
	v_add_u32_e32 v4, 0x100, v4
	global_atomic_add v4, v3, s[6:7]
	v_add_u32_e32 v4, 0x100, v4
	global_atomic_add v4, v3, s[6:7]
	v_add_u32_e32 v4, 0x100, v4
	global_atomic_add v4, v3, s[6:7]
	v_add_u32_e32 v4, 0x100, v4
	global_atomic_add v4, v3, s[6:7]
	v_add_u32_e32 v4, 0x100, v4
	global_atomic_add v4, v3, s[6:7]
	v_add_u32_e32 v4, 0x100, v4
	global_atomic_add v4, v3, s[6:7]
	v_add_u32_e32 v4, 0x100, v4
	global_atomic_add v4, v3, s[6:7]
	v_add_u32_e32 v4, 0x100, v4
	global_atomic_add v4, v3, s[6:7]
	v_add_u32_e32 v4, 0x100, v4
	global_atomic_add v4, v3, s[6:7]
	v_add_u32_e32 v4, 0x100, v4
	global_atomic_add v4, v3, s[6:7]
	v_add_u32_e32 v4, 0x100, v4
	global_atomic_add v4, v3, s[6:7]
	v_add_u32_e32 v4, 0x100, v4
	v_mov_b32_e32 v4, 0x7f000
	global_atomic_add v4, v3, s[30:31] offset:1280

.Lxb_done_8:
	s_or_b64 exec, exec, s[4:5]
	s_waitcnt lgkmcnt(0)
	s_barrier
.LBB0_1932:
	s_cmp_gt_i32 s66, 8
	s_cselect_b64 s[0:1], -1, 0
	s_cmp_lt_i32 s67, 9
	s_cselect_b64 s[2:3], -1, 0
	s_or_b64 s[0:1], s[0:1], s[2:3]
	s_and_b64 vcc, exec, s[0:1]
	s_cbranch_vccnz .LBB0_1992
	s_and_b32 s12, s78, 7
	s_lshr_b32 s2, s78, 3
	s_ashr_i32 s3, s64, 3
	s_cmpk_lt_u32 s78, 0x200
	s_cselect_b64 s[0:1], -1, 0
	s_add_u32 s4, s30, 0xab93e00
	s_addc_u32 s5, s31, 0
	s_add_u32 s6, s30, 0x1f13e00
	s_addc_u32 s7, s31, 0
	s_add_u32 s13, s30, 0x5393e00
	v_cndmask_b32_e64 v0, 0, 1, s[0:1]
	s_addc_u32 s14, s31, 0
	s_lshl_b32 s15, s12, 3
	s_mov_b32 s16, 0
	s_lshl_b32 s17, s12, 10
	v_cmp_ne_u32_e64 s[0:1], 1, v0
	v_mov_b32_e32 v97, 0
	s_mov_b32 s18, 0x10000
	s_mov_b32 s19, 0x20000
	s_mov_b32 s20, 0x30000
	s_movk_i32 s21, 0x90
	s_mov_b32 s22, 0xfffffc0
	s_mov_b32 s23, 0xab93000
	s_mov_b32 s24, 0xaba3000
	s_mov_b32 s25, 0xabb3000
	s_mov_b32 s26, 0xabc3000
	s_mov_b32 s27, 0x1f13000
	s_mov_b32 s33, 0x1f23000
	s_mov_b32 s34, 0x1f33000
	s_mov_b32 s35, 0x1f43000
	s_mov_b64 s[8:9], 0x100
	s_movk_i32 s36, 0x110
	s_movk_i32 s37, 0x2c00
	s_branch .LBB0_1935

.LBB0_2127:
	s_cmp_gt_u32 s67, 12
	s_cbranch_scc0 .LBB0_2177
	s_waitcnt vmcnt(0)
	s_waitcnt vmcnt(63) expcnt(7) lgkmcnt(15)
	s_barrier
	s_mov_b64 s[4:5], exec
	v_readlane_b32 s2, v251, 3
	v_readlane_b32 s3, v251, 4
	s_and_b64 s[2:3], s[4:5], s[2:3]
	s_mov_b64 exec, s[2:3]
	s_cbranch_execz .Lxb_done_12
	v_mov_b32_e32 v0, 0
	s_waitcnt vmcnt(0) expcnt(0) lgkmcnt(0)
	ds_read_b32 v2, v0
	ds_read_b32 v1, v0 offset:4
	v_readlane_b32 s0, v251, 2
	v_readlane_b32 s6, v251, 5
	v_readlane_b32 s7, v251, 6
	s_lshl_b32 s0, s0, 8
	s_add_u32 s8, s6, s0
	s_addc_u32 s9, s7, 0
	v_mov_b32_e32 v3, 1
	v_mov_b32_e32 v4, 0x1000
	s_nop 4
	global_atomic_add v3, v4, v3, s[8:9] offset:1024 sc0
	buffer_inv sc1
	s_sub_u32 s10, 11, s66
	s_add_u32 s11, s10, 1
	s_waitcnt lgkmcnt(0)
	v_readfirstlane_b32 s12, v2
	v_readfirstlane_b32 s13, v1
	s_mul_i32 s14, s12, s11
	s_mul_i32 s15, s13, s11
	s_waitcnt vmcnt(0)
	v_readfirstlane_b32 s16, v3
	s_add_u32 s16, s16, 1
	s_cmp_lg_u32 s16, s14
	s_cbranch_scc1 .Lxb_wait_12
	buffer_wbl2 sc1
	s_waitcnt vmcnt(0)
	v_mov_b32_e32 v3, 1
	v_mov_b32_e32 v4, 0x7f000
	global_atomic_add v3, v4, v3, s[30:31] offset:1024 sc0
	s_waitcnt vmcnt(0)
	v_readfirstlane_b32 s16, v3
	s_add_u32 s16, s16, 1
	s_cmp_lg_u32 s16, s15
	s_cbranch_scc1 .Lxb_wait_12
	v_mov_b32_e32 v3, 1
	v_mov_b32_e32 v4, 0x2400
	global_atomic_add v4, v3, s[6:7]
	v_add_u32_e32 v4, 0x100, v4
	global_atomic_add v4, v3, s[6:7]
	v_add_u32_e32 v4, 0x100, v4
	global_atomic_add v4, v3, s[6:7]
	v_add_u32_e32 v4, 0x100, v4
	global_atomic_add v4, v3, s[6:7]
	v_add_u32_e32 v4, 0x100, v4
	global_atomic_add v4, v3, s[6:7]
	v_add_u32_e32 v4, 0x100, v4
	global_atomic_add v4, v3, s[6:7]
	v_add_u32_e32 v4, 0x100, v4
	global_atomic_add v4, v3, s[6:7]
	v_add_u32_e32 v4, 0x100, v4
	global_atomic_add v4, v3, s[6:7]
	v_add_u32_e32 v4, 0x100, v4
	global_atomic_add v4, v3, s[6:7]
	v_add_u32_e32 v4, 0x100, v4
	global_atomic_add v4, v3, s[6:7]
	v_add_u32_e32 v4, 0x100, v4
	global_atomic_add v4, v3, s[6:7]
	v_add_u32_e32 v4, 0x100, v4
	global_atomic_add v4, v3, s[6:7]
	v_add_u32_e32 v4, 0x100, v4
	global_atomic_add v4, v3, s[6:7]
	v_add_u32_e32 v4, 0x100, v4
	global_atomic_add v4, v3, s[6:7]
	v_add_u32_e32 v4, 0x100, v4
	global_atomic_add v4, v3, s[6:7]
	v_add_u32_e32 v4, 0x100, v4
	global_atomic_add v4, v3, s[6:7]
	v_add_u32_e32 v4, 0x100, v4
	v_mov_b32_e32 v4, 0x7f000
	global_atomic_add v4, v3, s[30:31] offset:1280

.Lxb_done_12:
	s_or_b64 exec, exec, s[4:5]
	s_waitcnt lgkmcnt(0)
	s_barrier
.LBB0_2177:
	s_cmp_gt_i32 s66, 12
	s_cselect_b64 s[0:1], -1, 0
	s_cmp_lt_i32 s67, 13
	s_cselect_b64 s[2:3], -1, 0
	s_or_b64 s[0:1], s[0:1], s[2:3]
	s_and_b64 vcc, exec, s[0:1]
	s_cbranch_vccnz .LBB0_3154
	s_and_b32 s33, s78, 7
	s_lshr_b32 s3, s78, 3
	s_ashr_i32 s27, s64, 3
	s_cmpk_lt_u32 s78, 0x200
	s_cselect_b64 s[0:1], -1, 0
	s_add_u32 s16, s30, 0xc793e00
	s_addc_u32 s17, s31, 0
	s_add_u32 s18, s30, 0x2f93e00
	s_addc_u32 s19, s31, 0
	s_add_u32 s20, s30, 0x7fe00
	v_cndmask_b32_e64 v0, 0, 1, s[0:1]
	s_addc_u32 s21, s31, 0
	s_lshl_b32 s37, s33, 3
	s_mov_b32 s23, 0
	s_lshl_b32 s50, s78, 3
	v_cmp_ne_u32_e64 s[0:1], 1, v0
	v_mov_b32_e32 v97, 0
	s_mov_b32 s51, 0x10000
	s_mov_b32 s52, 0x20000
	s_mov_b32 s53, 0x30000
	s_movk_i32 s54, 0x90
	s_mov_b64 s[24:25], 0x100
	s_mov_b32 s26, 0x3e000000
	s_mov_b32 s36, 0x3db504f3
	s_movk_i32 s55, 0x110
	s_mov_b32 s56, 0
	s_branch .LBB0_2180

.LBB0_2206:
	v_ashrrev_i32_e32 v66, 1, v102
	v_lshrrev_b32_e32 v64, 3, v102
	v_and_b32_e32 v72, 4, v64
	v_add_u32_e32 v64, s60, v66
	v_bfe_u32 v73, v64, 6, 4
	v_lshlrev_b32_e32 v64, 1, v102
	v_and_b32_e32 v74, 62, v64
	v_cndmask_b32_e64 v64, 0, 1, s[10:11]
	s_and_b64 vcc, exec, s[8:9]
	v_cmp_ne_u32_e64 s[8:9], 1, v64
	s_cbranch_vccz .LBB0_2211
	s_and_b64 vcc, exec, s[8:9]
	s_cbranch_vccnz .LBB0_2209
	v_lshlrev_b32_e32 v175, 2, v74
	v_mov_b32_e32 v174, v72
	v_cndmask_b32_e64 v174, v174, v73, s[6:7]
	v_lshl_or_b32 v174, v174, 8, v175
	global_load_dwordx2 v[110:111], v174, s[20:21]
	v_or_b32_e32 v174, 1, v72
	v_cndmask_b32_e64 v174, v174, v73, s[6:7]
	v_lshl_or_b32 v174, v174, 8, v175
	global_load_dwordx2 v[112:113], v174, s[20:21]
	v_or_b32_e32 v174, 2, v72
	v_cndmask_b32_e64 v174, v174, v73, s[6:7]
	v_lshl_or_b32 v174, v174, 8, v175
	global_load_dwordx2 v[114:115], v174, s[20:21]
	v_or_b32_e32 v174, 3, v72
	v_cndmask_b32_e64 v174, v174, v73, s[6:7]
	v_lshl_or_b32 v174, v174, 8, v175
	global_load_dwordx2 v[116:117], v174, s[20:21]
	v_or_b32_e32 v174, 8, v72
	v_cndmask_b32_e64 v174, v174, v73, s[6:7]
	v_lshl_or_b32 v174, v174, 8, v175
	global_load_dwordx2 v[118:119], v174, s[20:21]
	v_or_b32_e32 v174, 9, v72
	v_cndmask_b32_e64 v174, v174, v73, s[6:7]
	v_lshl_or_b32 v174, v174, 8, v175
	global_load_dwordx2 v[120:121], v174, s[20:21]
	v_or_b32_e32 v174, 10, v72
	v_cndmask_b32_e64 v174, v174, v73, s[6:7]
	v_lshl_or_b32 v174, v174, 8, v175
	global_load_dwordx2 v[122:123], v174, s[20:21]
	v_or_b32_e32 v174, 11, v72
	v_cndmask_b32_e64 v174, v174, v73, s[6:7]
	v_lshl_or_b32 v174, v174, 8, v175
	global_load_dwordx2 v[124:125], v174, s[20:21]
	v_or_b32_e32 v174, 16, v72
	v_cndmask_b32_e64 v174, v174, v73, s[6:7]
	v_lshl_or_b32 v174, v174, 8, v175
	global_load_dwordx2 v[126:127], v174, s[20:21]
	v_or_b32_e32 v174, 17, v72
	v_cndmask_b32_e64 v174, v174, v73, s[6:7]
	v_lshl_or_b32 v174, v174, 8, v175
	global_load_dwordx2 v[128:129], v174, s[20:21]
	v_or_b32_e32 v174, 18, v72
	v_cndmask_b32_e64 v174, v174, v73, s[6:7]
	v_lshl_or_b32 v174, v174, 8, v175
	global_load_dwordx2 v[130:131], v174, s[20:21]
	v_or_b32_e32 v174, 19, v72
	v_cndmask_b32_e64 v174, v174, v73, s[6:7]
	v_lshl_or_b32 v174, v174, 8, v175
	global_load_dwordx2 v[132:133], v174, s[20:21]
	v_or_b32_e32 v174, 24, v72
	v_cndmask_b32_e64 v174, v174, v73, s[6:7]
	v_lshl_or_b32 v174, v174, 8, v175
	global_load_dwordx2 v[134:135], v174, s[20:21]
	v_or_b32_e32 v174, 25, v72
	v_cndmask_b32_e64 v174, v174, v73, s[6:7]
	v_lshl_or_b32 v174, v174, 8, v175
	global_load_dwordx2 v[136:137], v174, s[20:21]
	v_or_b32_e32 v174, 26, v72
	v_cndmask_b32_e64 v174, v174, v73, s[6:7]
	v_lshl_or_b32 v174, v174, 8, v175
	global_load_dwordx2 v[138:139], v174, s[20:21]
	v_or_b32_e32 v174, 27, v72
	v_cndmask_b32_e64 v174, v174, v73, s[6:7]
	v_lshl_or_b32 v174, v174, 8, v175
	global_load_dwordx2 v[140:141], v174, s[20:21]
	v_or_b32_e32 v174, 32, v72
	v_cndmask_b32_e64 v174, v174, v73, s[6:7]
	v_lshl_or_b32 v174, v174, 8, v175
	global_load_dwordx2 v[142:143], v174, s[20:21]
	v_or_b32_e32 v174, 33, v72
	v_cndmask_b32_e64 v174, v174, v73, s[6:7]
	v_lshl_or_b32 v174, v174, 8, v175
	global_load_dwordx2 v[144:145], v174, s[20:21]
	v_or_b32_e32 v174, 34, v72
	v_cndmask_b32_e64 v174, v174, v73, s[6:7]
	v_lshl_or_b32 v174, v174, 8, v175
	global_load_dwordx2 v[146:147], v174, s[20:21]
	v_or_b32_e32 v174, 35, v72
	v_cndmask_b32_e64 v174, v174, v73, s[6:7]
	v_lshl_or_b32 v174, v174, 8, v175
	global_load_dwordx2 v[148:149], v174, s[20:21]
	v_or_b32_e32 v174, 40, v72
	v_cndmask_b32_e64 v174, v174, v73, s[6:7]
	v_lshl_or_b32 v174, v174, 8, v175
	global_load_dwordx2 v[150:151], v174, s[20:21]
	v_or_b32_e32 v174, 41, v72
	v_cndmask_b32_e64 v174, v174, v73, s[6:7]
	v_lshl_or_b32 v174, v174, 8, v175
	global_load_dwordx2 v[152:153], v174, s[20:21]
	v_or_b32_e32 v174, 42, v72
	v_cndmask_b32_e64 v174, v174, v73, s[6:7]
	v_lshl_or_b32 v174, v174, 8, v175
	global_load_dwordx2 v[154:155], v174, s[20:21]
	v_or_b32_e32 v174, 43, v72
	v_cndmask_b32_e64 v174, v174, v73, s[6:7]
	v_lshl_or_b32 v174, v174, 8, v175
	global_load_dwordx2 v[156:157], v174, s[20:21]
	v_or_b32_e32 v174, 48, v72
	v_cndmask_b32_e64 v174, v174, v73, s[6:7]
	v_lshl_or_b32 v174, v174, 8, v175
	global_load_dwordx2 v[158:159], v174, s[20:21]
	v_or_b32_e32 v174, 49, v72
	v_cndmask_b32_e64 v174, v174, v73, s[6:7]
	v_lshl_or_b32 v174, v174, 8, v175
	global_load_dwordx2 v[160:161], v174, s[20:21]
	v_or_b32_e32 v174, 50, v72
	v_cndmask_b32_e64 v174, v174, v73, s[6:7]
	v_lshl_or_b32 v174, v174, 8, v175
	global_load_dwordx2 v[162:163], v174, s[20:21]
	v_or_b32_e32 v174, 51, v72
	v_cndmask_b32_e64 v174, v174, v73, s[6:7]
	v_lshl_or_b32 v174, v174, 8, v175
	global_load_dwordx2 v[164:165], v174, s[20:21]
	v_or_b32_e32 v174, 56, v72
	v_cndmask_b32_e64 v174, v174, v73, s[6:7]
	v_lshl_or_b32 v174, v174, 8, v175
	global_load_dwordx2 v[166:167], v174, s[20:21]
	v_or_b32_e32 v174, 57, v72
	v_cndmask_b32_e64 v174, v174, v73, s[6:7]
	v_lshl_or_b32 v174, v174, 8, v175
	global_load_dwordx2 v[168:169], v174, s[20:21]
	v_or_b32_e32 v174, 58, v72
	v_cndmask_b32_e64 v174, v174, v73, s[6:7]
	v_lshl_or_b32 v174, v174, 8, v175
	global_load_dwordx2 v[170:171], v174, s[20:21]
	v_or_b32_e32 v174, 59, v72
	v_cndmask_b32_e64 v174, v174, v73, s[6:7]
	v_lshl_or_b32 v174, v174, 8, v175
	global_load_dwordx2 v[172:173], v174, s[20:21]
	s_waitcnt vmcnt(0)
	v_mov_b64_e32 v[64:65], v[110:111]
	s_waitcnt vmcnt(0)
	v_pk_mul_f32 v[70:71], v[32:33], v[64:65] op_sel:[0,1] op_sel_hi:[0,0]
	v_pk_mul_f32 v[68:69], v[48:49], v[64:65]
	v_pk_fma_f32 v[64:65], v[48:49], v[64:65], v[70:71] op_sel_hi:[0,1,1]
	v_sub_f32_e32 v64, v68, v70
	s_branch .LBB0_2210

.LBB0_2227:
	s_and_b64 vcc, exec, s[14:15]
	s_cbranch_vccz .LBB0_2235
	s_and_b64 vcc, exec, s[8:9]
	s_cbranch_vccnz .LBB0_2237
	v_mov_b64_e32 v[70:71], v[112:113]
	s_waitcnt vmcnt(0)
	v_pk_mul_f32 v[78:79], v[32:33], v[70:71] op_sel:[1,1] op_sel_hi:[1,0]
	v_pk_mul_f32 v[76:77], v[48:49], v[70:71] op_sel:[1,0]
	v_pk_fma_f32 v[70:71], v[48:49], v[70:71], v[78:79] op_sel:[1,0,0]
	s_nop 0
	v_sub_f32_e32 v70, v76, v78
	s_branch .LBB0_2238

.LBB0_2253:
	s_and_b64 vcc, exec, s[14:15]
	s_cbranch_vccz .LBB0_2261
	s_and_b64 vcc, exec, s[8:9]
	s_cbranch_vccnz .LBB0_2263
	v_mov_b64_e32 v[32:33], v[114:115]
	s_waitcnt vmcnt(0)
	v_pk_mul_f32 v[76:77], v[34:35], v[32:33] op_sel:[0,1] op_sel_hi:[0,0]
	v_pk_mul_f32 v[48:49], v[50:51], v[32:33]
	v_pk_fma_f32 v[32:33], v[50:51], v[32:33], v[76:77] op_sel_hi:[0,1,1]
	v_sub_f32_e32 v32, v48, v76
	s_branch .LBB0_2264

.LBB0_2279:
	s_and_b64 vcc, exec, s[14:15]
	s_cbranch_vccz .LBB0_2287
	s_and_b64 vcc, exec, s[8:9]
	s_cbranch_vccnz .LBB0_2289
	v_mov_b64_e32 v[48:49], v[116:117]
	v_mov_b32_e32 v50, v35
	v_mov_b32_e32 v34, v51
	s_waitcnt vmcnt(0)
	v_pk_mul_f32 v[78:79], v[50:51], v[48:49] op_sel:[0,1] op_sel_hi:[0,0]
	v_pk_mul_f32 v[76:77], v[34:35], v[48:49] op_sel_hi:[0,1]
	v_pk_fma_f32 v[48:49], v[34:35], v[48:49], v[78:79] op_sel_hi:[0,1,1]
	v_sub_f32_e32 v48, v76, v78
	s_branch .LBB0_2290

.LBB0_2299:
	s_and_b64 vcc, exec, s[34:35]
	s_cbranch_vccz .LBB0_2315
	s_and_b64 vcc, exec, s[8:9]
	s_cbranch_vccnz .LBB0_2317
	v_mov_b64_e32 v[32:33], v[118:119]
	s_waitcnt vmcnt(0)
	v_pk_mul_f32 v[48:49], v[36:37], v[32:33] op_sel:[0,1] op_sel_hi:[0,0]
	v_pk_mul_f32 v[34:35], v[52:53], v[32:33]
	v_pk_fma_f32 v[32:33], v[52:53], v[32:33], v[48:49] op_sel_hi:[0,1,1]
	v_sub_f32_e32 v32, v34, v48
	s_branch .LBB0_2318

.LBB0_2333:
	s_and_b64 vcc, exec, s[34:35]
	s_cbranch_vccz .LBB0_2341
	s_and_b64 vcc, exec, s[8:9]
	s_cbranch_vccnz .LBB0_2343
	v_mov_b64_e32 v[34:35], v[120:121]
	v_mov_b32_e32 v48, v37
	v_mov_b32_e32 v36, v53
	s_waitcnt vmcnt(0)
	v_pk_mul_f32 v[48:49], v[48:49], v[34:35] op_sel:[0,1] op_sel_hi:[0,0]
	v_pk_mul_f32 v[68:69], v[36:37], v[34:35] op_sel_hi:[0,1]
	v_pk_fma_f32 v[34:35], v[36:37], v[34:35], v[48:49] op_sel_hi:[0,1,1]
	v_sub_f32_e32 v34, v68, v48
	s_branch .LBB0_2344

.LBB0_2359:
	s_and_b64 vcc, exec, s[34:35]
	s_cbranch_vccz .LBB0_2367
	s_and_b64 vcc, exec, s[8:9]
	s_cbranch_vccnz .LBB0_2369
	v_mov_b64_e32 v[36:37], v[122:123]
	s_waitcnt vmcnt(0)
	v_pk_mul_f32 v[52:53], v[38:39], v[36:37] op_sel:[0,1] op_sel_hi:[0,0]
	v_pk_mul_f32 v[48:49], v[54:55], v[36:37]
	v_pk_fma_f32 v[36:37], v[54:55], v[36:37], v[52:53] op_sel_hi:[0,1,1]
	v_sub_f32_e32 v36, v48, v52
	s_branch .LBB0_2370

.LBB0_2385:
	s_and_b64 vcc, exec, s[34:35]
	s_cbranch_vccz .LBB0_2393
	s_and_b64 vcc, exec, s[8:9]
	s_cbranch_vccnz .LBB0_2395
	v_mov_b64_e32 v[48:49], v[124:125]
	v_mov_b32_e32 v52, v39
	v_mov_b32_e32 v38, v55
	s_waitcnt vmcnt(0)
	v_pk_mul_f32 v[52:53], v[52:53], v[48:49] op_sel:[0,1] op_sel_hi:[0,0]
	v_pk_mul_f32 v[68:69], v[38:39], v[48:49] op_sel_hi:[0,1]
	v_pk_fma_f32 v[48:49], v[38:39], v[48:49], v[52:53] op_sel_hi:[0,1,1]
	v_sub_f32_e32 v48, v68, v52
	s_branch .LBB0_2396

.LBB0_2403:
	s_and_b64 vcc, exec, s[34:35]
	s_cbranch_vccz .LBB0_2421
	s_and_b64 vcc, exec, s[8:9]
	s_cbranch_vccnz .LBB0_2423
	v_mov_b64_e32 v[32:33], v[126:127]
	s_waitcnt vmcnt(0)
	v_pk_mul_f32 v[36:37], v[40:41], v[32:33] op_sel:[0,1] op_sel_hi:[0,0]
	v_pk_mul_f32 v[34:35], v[56:57], v[32:33]
	v_pk_fma_f32 v[32:33], v[56:57], v[32:33], v[36:37] op_sel_hi:[0,1,1]
	v_sub_f32_e32 v32, v34, v36
	s_branch .LBB0_2424

.LBB0_2439:
	s_and_b64 vcc, exec, s[34:35]
	s_cbranch_vccz .LBB0_2447
	s_and_b64 vcc, exec, s[8:9]
	s_cbranch_vccnz .LBB0_2449
	v_mov_b64_e32 v[34:35], v[128:129]
	v_mov_b32_e32 v38, v41
	v_mov_b32_e32 v36, v57
	s_waitcnt vmcnt(0)
	v_pk_mul_f32 v[38:39], v[38:39], v[34:35] op_sel:[0,1] op_sel_hi:[0,0]
	v_pk_mul_f32 v[48:49], v[36:37], v[34:35] op_sel_hi:[0,1]
	v_pk_fma_f32 v[34:35], v[36:37], v[34:35], v[38:39] op_sel_hi:[0,1,1]
	v_sub_f32_e32 v34, v48, v38
	s_branch .LBB0_2450

.LBB0_2465:
	s_and_b64 vcc, exec, s[34:35]
	s_cbranch_vccz .LBB0_2473
	s_and_b64 vcc, exec, s[8:9]
	s_cbranch_vccnz .LBB0_2475
	v_mov_b64_e32 v[36:37], v[130:131]
	s_waitcnt vmcnt(0)
	v_pk_mul_f32 v[40:41], v[42:43], v[36:37] op_sel:[0,1] op_sel_hi:[0,0]
	v_pk_mul_f32 v[38:39], v[58:59], v[36:37]
	v_pk_fma_f32 v[36:37], v[58:59], v[36:37], v[40:41] op_sel_hi:[0,1,1]
	v_sub_f32_e32 v36, v38, v40
	s_branch .LBB0_2476

.LBB0_2491:
	s_and_b64 vcc, exec, s[34:35]
	s_cbranch_vccz .LBB0_2499
	s_and_b64 vcc, exec, s[8:9]
	s_cbranch_vccnz .LBB0_2501
	v_mov_b64_e32 v[38:39], v[132:133]
	v_mov_b32_e32 v42, v43
	v_mov_b32_e32 v40, v59
	s_waitcnt vmcnt(0)
	v_pk_mul_f32 v[52:53], v[42:43], v[38:39] op_sel:[0,1] op_sel_hi:[0,0]
	v_pk_mul_f32 v[48:49], v[40:41], v[38:39] op_sel_hi:[0,1]
	v_pk_fma_f32 v[38:39], v[40:41], v[38:39], v[52:53] op_sel_hi:[0,1,1]
	v_sub_f32_e32 v38, v48, v52
	s_branch .LBB0_2502

.LBB0_2509:
	s_and_b64 vcc, exec, s[34:35]
	s_cbranch_vccz .LBB0_2527
	s_and_b64 vcc, exec, s[8:9]
	s_cbranch_vccnz .LBB0_2529
	v_mov_b64_e32 v[32:33], v[134:135]
	s_waitcnt vmcnt(0)
	v_pk_mul_f32 v[36:37], v[44:45], v[32:33] op_sel:[0,1] op_sel_hi:[0,0]
	v_pk_mul_f32 v[34:35], v[60:61], v[32:33]
	v_pk_fma_f32 v[32:33], v[60:61], v[32:33], v[36:37] op_sel_hi:[0,1,1]
	v_sub_f32_e32 v32, v34, v36
	s_branch .LBB0_2530

.LBB0_2545:
	s_and_b64 vcc, exec, s[34:35]
	s_cbranch_vccz .LBB0_2553
	s_and_b64 vcc, exec, s[8:9]
	s_cbranch_vccnz .LBB0_2555
	v_mov_b64_e32 v[34:35], v[136:137]
	v_mov_b32_e32 v38, v45
	v_mov_b32_e32 v36, v61
	s_waitcnt vmcnt(0)
	v_pk_mul_f32 v[38:39], v[38:39], v[34:35] op_sel:[0,1] op_sel_hi:[0,0]
	v_pk_mul_f32 v[40:41], v[36:37], v[34:35] op_sel_hi:[0,1]
	v_pk_fma_f32 v[34:35], v[36:37], v[34:35], v[38:39] op_sel_hi:[0,1,1]
	v_sub_f32_e32 v34, v40, v38
	s_branch .LBB0_2556

.LBB0_2571:
	s_and_b64 vcc, exec, s[34:35]
	s_cbranch_vccz .LBB0_2579
	s_and_b64 vcc, exec, s[8:9]
	s_cbranch_vccnz .LBB0_2581
	v_mov_b64_e32 v[36:37], v[138:139]
	s_waitcnt vmcnt(0)
	v_pk_mul_f32 v[40:41], v[46:47], v[36:37] op_sel:[0,1] op_sel_hi:[0,0]
	v_pk_mul_f32 v[38:39], v[62:63], v[36:37]
	v_pk_fma_f32 v[36:37], v[62:63], v[36:37], v[40:41] op_sel_hi:[0,1,1]
	v_sub_f32_e32 v36, v38, v40
	s_branch .LBB0_2582

.LBB0_2597:
	s_and_b64 vcc, exec, s[34:35]
	s_cbranch_vccz .LBB0_2605
	s_and_b64 vcc, exec, s[8:9]
	s_cbranch_vccnz .LBB0_2607
	v_mov_b64_e32 v[38:39], v[140:141]
	v_mov_b32_e32 v42, v47
	v_mov_b32_e32 v40, v63
	s_waitcnt vmcnt(0)
	v_pk_mul_f32 v[42:43], v[42:43], v[38:39] op_sel:[0,1] op_sel_hi:[0,0]
	v_pk_mul_f32 v[44:45], v[40:41], v[38:39] op_sel_hi:[0,1]
	v_pk_fma_f32 v[38:39], v[40:41], v[38:39], v[42:43] op_sel_hi:[0,1,1]
	v_sub_f32_e32 v38, v44, v42
	s_branch .LBB0_2608

.LBB0_2615:
	s_and_b64 vcc, exec, s[34:35]
	s_cbranch_vccz .LBB0_2633
	s_and_b64 vcc, exec, s[8:9]
	s_cbranch_vccnz .LBB0_2635
	v_mov_b64_e32 v[32:33], v[142:143]
	s_waitcnt vmcnt(0)
	v_pk_mul_f32 v[36:37], v[0:1], v[32:33] op_sel:[0,1] op_sel_hi:[0,0]
	v_pk_mul_f32 v[34:35], v[16:17], v[32:33]
	v_pk_fma_f32 v[32:33], v[16:17], v[32:33], v[36:37] op_sel_hi:[0,1,1]
	v_sub_f32_e32 v32, v34, v36
	s_branch .LBB0_2636

.LBB0_2651:
	s_and_b64 vcc, exec, s[34:35]
	s_cbranch_vccz .LBB0_2659
	s_and_b64 vcc, exec, s[8:9]
	s_cbranch_vccnz .LBB0_2661
	v_mov_b64_e32 v[34:35], v[144:145]
	s_waitcnt vmcnt(0)
	v_pk_mul_f32 v[38:39], v[0:1], v[34:35] op_sel:[1,1] op_sel_hi:[1,0]
	v_pk_mul_f32 v[36:37], v[16:17], v[34:35] op_sel:[1,0]
	v_pk_fma_f32 v[34:35], v[16:17], v[34:35], v[38:39] op_sel:[1,0,0]
	s_nop 0
	v_sub_f32_e32 v34, v36, v38
	s_branch .LBB0_2662

.LBB0_2677:
	s_and_b64 vcc, exec, s[34:35]
	s_cbranch_vccz .LBB0_2685
	s_and_b64 vcc, exec, s[8:9]
	s_cbranch_vccnz .LBB0_2687
	v_mov_b64_e32 v[0:1], v[146:147]
	s_waitcnt vmcnt(0)
	v_pk_mul_f32 v[36:37], v[2:3], v[0:1] op_sel:[0,1] op_sel_hi:[0,0]
	v_pk_mul_f32 v[16:17], v[18:19], v[0:1]
	v_pk_fma_f32 v[0:1], v[18:19], v[0:1], v[36:37] op_sel_hi:[0,1,1]
	v_sub_f32_e32 v0, v16, v36
	s_branch .LBB0_2688

.LBB0_2703:
	s_and_b64 vcc, exec, s[34:35]
	s_cbranch_vccz .LBB0_2711
	s_and_b64 vcc, exec, s[8:9]
	s_cbranch_vccnz .LBB0_2713
	v_mov_b64_e32 v[16:17], v[148:149]
	v_mov_b32_e32 v18, v3
	v_mov_b32_e32 v2, v19
	s_waitcnt vmcnt(0)
	v_pk_mul_f32 v[38:39], v[18:19], v[16:17] op_sel:[0,1] op_sel_hi:[0,0]
	v_pk_mul_f32 v[36:37], v[2:3], v[16:17] op_sel_hi:[0,1]
	v_pk_fma_f32 v[16:17], v[2:3], v[16:17], v[38:39] op_sel_hi:[0,1,1]
	v_sub_f32_e32 v16, v36, v38
	s_branch .LBB0_2714

.LBB0_2721:
	s_and_b64 vcc, exec, s[34:35]
	s_cbranch_vccz .LBB0_2739
	s_and_b64 vcc, exec, s[8:9]
	s_cbranch_vccnz .LBB0_2741
	v_mov_b64_e32 v[0:1], v[150:151]
	s_waitcnt vmcnt(0)
	v_pk_mul_f32 v[16:17], v[4:5], v[0:1] op_sel:[0,1] op_sel_hi:[0,0]
	v_pk_mul_f32 v[2:3], v[20:21], v[0:1]
	v_pk_fma_f32 v[0:1], v[20:21], v[0:1], v[16:17] op_sel_hi:[0,1,1]
	v_sub_f32_e32 v0, v2, v16
	s_branch .LBB0_2742

.LBB0_2757:
	s_and_b64 vcc, exec, s[34:35]
	s_cbranch_vccz .LBB0_2765
	s_and_b64 vcc, exec, s[8:9]
	s_cbranch_vccnz .LBB0_2767
	v_mov_b64_e32 v[2:3], v[152:153]
	v_mov_b32_e32 v16, v5
	v_mov_b32_e32 v4, v21
	s_waitcnt vmcnt(0)
	v_pk_mul_f32 v[16:17], v[16:17], v[2:3] op_sel:[0,1] op_sel_hi:[0,0]
	v_pk_mul_f32 v[18:19], v[4:5], v[2:3] op_sel_hi:[0,1]
	v_pk_fma_f32 v[2:3], v[4:5], v[2:3], v[16:17] op_sel_hi:[0,1,1]
	v_sub_f32_e32 v2, v18, v16
	s_branch .LBB0_2768

.LBB0_2783:
	s_and_b64 vcc, exec, s[34:35]
	s_cbranch_vccz .LBB0_2791
	s_and_b64 vcc, exec, s[8:9]
	s_cbranch_vccnz .LBB0_2793
	v_mov_b64_e32 v[4:5], v[154:155]
	s_waitcnt vmcnt(0)
	v_pk_mul_f32 v[18:19], v[6:7], v[4:5] op_sel:[0,1] op_sel_hi:[0,0]
	v_pk_mul_f32 v[16:17], v[22:23], v[4:5]
	v_pk_fma_f32 v[4:5], v[22:23], v[4:5], v[18:19] op_sel_hi:[0,1,1]
	v_sub_f32_e32 v4, v16, v18
	s_branch .LBB0_2794

.LBB0_2809:
	s_and_b64 vcc, exec, s[34:35]
	s_cbranch_vccz .LBB0_2817
	s_and_b64 vcc, exec, s[8:9]
	s_cbranch_vccnz .LBB0_2819
	v_mov_b64_e32 v[16:17], v[156:157]
	v_mov_b32_e32 v18, v7
	v_mov_b32_e32 v6, v23
	s_waitcnt vmcnt(0)
	v_pk_mul_f32 v[18:19], v[18:19], v[16:17] op_sel:[0,1] op_sel_hi:[0,0]
	v_pk_mul_f32 v[20:21], v[6:7], v[16:17] op_sel_hi:[0,1]
	v_pk_fma_f32 v[16:17], v[6:7], v[16:17], v[18:19] op_sel_hi:[0,1,1]
	v_sub_f32_e32 v16, v20, v18
	s_branch .LBB0_2820

.LBB0_2827:
	s_and_b64 vcc, exec, s[34:35]
	s_cbranch_vccz .LBB0_2845
	s_and_b64 vcc, exec, s[8:9]
	s_cbranch_vccnz .LBB0_2847
	v_mov_b64_e32 v[0:1], v[158:159]
	s_waitcnt vmcnt(0)
	v_pk_mul_f32 v[4:5], v[8:9], v[0:1] op_sel:[0,1] op_sel_hi:[0,0]
	v_pk_mul_f32 v[2:3], v[24:25], v[0:1]
	v_pk_fma_f32 v[0:1], v[24:25], v[0:1], v[4:5] op_sel_hi:[0,1,1]
	v_sub_f32_e32 v0, v2, v4
	s_branch .LBB0_2848

.LBB0_2863:
	s_and_b64 vcc, exec, s[34:35]
	s_cbranch_vccz .LBB0_2871
	s_and_b64 vcc, exec, s[8:9]
	s_cbranch_vccnz .LBB0_2873
	v_mov_b64_e32 v[2:3], v[160:161]
	v_mov_b32_e32 v6, v9
	v_mov_b32_e32 v4, v25
	s_waitcnt vmcnt(0)
	v_pk_mul_f32 v[6:7], v[6:7], v[2:3] op_sel:[0,1] op_sel_hi:[0,0]
	v_pk_mul_f32 v[16:17], v[4:5], v[2:3] op_sel_hi:[0,1]
	v_pk_fma_f32 v[2:3], v[4:5], v[2:3], v[6:7] op_sel_hi:[0,1,1]
	v_sub_f32_e32 v2, v16, v6
	s_branch .LBB0_2874

.LBB0_2889:
	s_and_b64 vcc, exec, s[34:35]
	s_cbranch_vccz .LBB0_2897
	s_and_b64 vcc, exec, s[8:9]
	s_cbranch_vccnz .LBB0_2899
	v_mov_b64_e32 v[4:5], v[162:163]
	s_waitcnt vmcnt(0)
	v_pk_mul_f32 v[8:9], v[10:11], v[4:5] op_sel:[0,1] op_sel_hi:[0,0]
	v_pk_mul_f32 v[6:7], v[26:27], v[4:5]
	v_pk_fma_f32 v[4:5], v[26:27], v[4:5], v[8:9] op_sel_hi:[0,1,1]
	v_sub_f32_e32 v4, v6, v8
	s_branch .LBB0_2900

.LBB0_2915:
	s_and_b64 vcc, exec, s[34:35]
	s_cbranch_vccz .LBB0_2923
	s_and_b64 vcc, exec, s[8:9]
	s_cbranch_vccnz .LBB0_2925
	v_mov_b64_e32 v[6:7], v[164:165]
	v_mov_b32_e32 v10, v11
	v_mov_b32_e32 v8, v27
	s_waitcnt vmcnt(0)
	v_pk_mul_f32 v[18:19], v[10:11], v[6:7] op_sel:[0,1] op_sel_hi:[0,0]
	v_pk_mul_f32 v[16:17], v[8:9], v[6:7] op_sel_hi:[0,1]
	v_pk_fma_f32 v[6:7], v[8:9], v[6:7], v[18:19] op_sel_hi:[0,1,1]
	v_sub_f32_e32 v6, v16, v18
	s_branch .LBB0_2926

.LBB0_2933:
	s_and_b64 vcc, exec, s[34:35]
	s_cbranch_vccz .LBB0_2951
	s_and_b64 vcc, exec, s[8:9]
	s_cbranch_vccnz .LBB0_2953
	v_mov_b64_e32 v[0:1], v[166:167]
	s_waitcnt vmcnt(0)
	v_pk_mul_f32 v[4:5], v[12:13], v[0:1] op_sel:[0,1] op_sel_hi:[0,0]
	v_pk_mul_f32 v[2:3], v[28:29], v[0:1]
	v_pk_fma_f32 v[0:1], v[28:29], v[0:1], v[4:5] op_sel_hi:[0,1,1]
	v_sub_f32_e32 v0, v2, v4
	s_branch .LBB0_2954

.LBB0_2969:
	s_and_b64 vcc, exec, s[34:35]
	s_cbranch_vccz .LBB0_2977
	s_and_b64 vcc, exec, s[8:9]
	s_cbranch_vccnz .LBB0_2979
	v_mov_b64_e32 v[2:3], v[168:169]
	v_mov_b32_e32 v6, v13
	v_mov_b32_e32 v4, v29
	s_waitcnt vmcnt(0)
	v_pk_mul_f32 v[6:7], v[6:7], v[2:3] op_sel:[0,1] op_sel_hi:[0,0]
	v_pk_mul_f32 v[8:9], v[4:5], v[2:3] op_sel_hi:[0,1]
	v_pk_fma_f32 v[2:3], v[4:5], v[2:3], v[6:7] op_sel_hi:[0,1,1]
	v_sub_f32_e32 v2, v8, v6
	s_branch .LBB0_2980

.LBB0_2995:
	s_and_b64 vcc, exec, s[34:35]
	s_cbranch_vccz .LBB0_3003
	s_and_b64 vcc, exec, s[8:9]
	s_cbranch_vccnz .LBB0_3005
	v_mov_b64_e32 v[4:5], v[170:171]
	s_waitcnt vmcnt(0)
	v_pk_mul_f32 v[8:9], v[14:15], v[4:5] op_sel:[0,1] op_sel_hi:[0,0]
	v_pk_mul_f32 v[6:7], v[30:31], v[4:5]
	v_pk_fma_f32 v[4:5], v[30:31], v[4:5], v[8:9] op_sel_hi:[0,1,1]
	v_sub_f32_e32 v4, v6, v8
	s_branch .LBB0_3006

.LBB0_3021:
	s_and_b64 vcc, exec, s[12:13]
	s_cbranch_vccz .LBB0_3029
	s_and_b64 vcc, exec, s[8:9]
	s_cbranch_vccnz .LBB0_3031
	v_mov_b64_e32 v[6:7], v[172:173]
	v_mov_b32_e32 v10, v15
	v_mov_b32_e32 v8, v31
	s_waitcnt vmcnt(0)
	v_pk_mul_f32 v[10:11], v[10:11], v[6:7] op_sel:[0,1] op_sel_hi:[0,0]
	v_pk_mul_f32 v[12:13], v[8:9], v[6:7] op_sel_hi:[0,1]
	v_pk_fma_f32 v[6:7], v[8:9], v[6:7], v[10:11] op_sel_hi:[0,1,1]
	v_sub_f32_e32 v6, v12, v10
	s_branch .LBB0_3032

.LBB0_3542:
	s_or_b32 s5, s5, s4
	s_lshl_b32 s5, s5, 2
	s_or_b32 s94, s5, s2
	v_cndmask_b32_e64 v100, v98, v99, s[0:1]
	s_lshl_b64 s[8:9], s[94:95], 15
	v_lshl_add_u64 v[96:97], v[50:51], 0, s[8:9]
	v_pk_mul_f32 v[14:15], v[100:101], v[52:53] op_sel_hi:[0,1]
	v_pk_mul_f32 v[16:17], v[100:101], v[38:39] op_sel_hi:[0,1]
	v_cvt_pk_bf16_f32 v14, v14, v15
	v_cvt_pk_bf16_f32 v15, v16, v17
	v_pk_mul_f32 v[16:17], v[100:101], v[54:55] op_sel_hi:[0,1]
	v_pk_mul_f32 v[18:19], v[100:101], v[40:41] op_sel_hi:[0,1]
	v_lshl_add_u64 v[94:95], v[96:97], 0, v[4:5]
	v_cvt_pk_bf16_f32 v16, v16, v17
	v_cvt_pk_bf16_f32 v17, v18, v19
	global_load_dwordx4 v[144:147], v[94:95], off
	v_lshl_add_u64 v[178:179], v[96:97], 0, v[56:57]
	global_load_dwordx4 v[148:151], v[178:179], off
	v_lshl_add_u64 v[180:181], v[96:97], 0, v[66:67]
	global_load_dwordx4 v[152:155], v[180:181], off
	v_lshl_add_u64 v[182:183], v[96:97], 0, v[58:59]
	global_load_dwordx4 v[156:159], v[182:183], off
	v_lshl_add_u64 v[184:185], v[96:97], 0, v[68:69]
	global_load_dwordx4 v[160:163], v[184:185], off
	v_lshl_add_u64 v[186:187], v[96:97], 0, v[60:61]
	global_load_dwordx4 v[164:167], v[186:187], off
	v_lshl_add_u64 v[188:189], v[96:97], 0, v[62:63]
	global_load_dwordx4 v[168:171], v[188:189], off
	v_lshl_add_u64 v[190:191], v[96:97], 0, v[64:65]
	global_load_dwordx4 v[172:175], v[190:191], off
	v_lshl_add_u64 v[102:103], v[96:97], 0, 64
	s_mov_b64 s[8:9], 0xc0
	s_mov_b32 s5, 1
	s_and_b64 vcc, exec, s[0:1]
	s_mov_b64 s[0:1], 0
	s_waitcnt vmcnt(7)
	v_mfma_f32_16x16x32_bf16 v[6:9], v[144:147], v[14:17], v[6:9]
	s_nop 0
	s_waitcnt vmcnt(6)
	v_mfma_f32_16x16x32_bf16 v[10:13], v[148:151], v[14:17], v[10:13]
	s_waitcnt vmcnt(5)
	v_mfma_f32_16x16x32_bf16 v[34:37], v[152:155], v[14:17], v[42:45]
	s_nop 2
	s_waitcnt vmcnt(4)
	v_mfma_f32_16x16x32_bf16 v[18:21], v[156:159], v[14:17], v[30:33]
	s_nop 2
	s_waitcnt vmcnt(3)
	v_mfma_f32_16x16x32_bf16 v[0:3], v[160:163], v[14:17], v[0:3]
	v_mul_f32_e64 v42, v100, v76
	v_mul_f32_e64 v43, v100, v77
	s_waitcnt vmcnt(2)
	v_mfma_f32_16x16x32_bf16 v[26:29], v[164:167], v[14:17], v[26:29]
	s_waitcnt vmcnt(1)
	v_mfma_f32_16x16x32_bf16 v[22:25], v[168:171], v[14:17], v[22:25]
	s_waitcnt vmcnt(0)
	v_mfma_f32_16x16x32_bf16 v[30:33], v[172:175], v[14:17], v[46:49]
	v_mul_f32_e64 v14, v100, v70
	v_mul_f32_e64 v15, v100, v71
	v_pk_mul_f32 v[16:17], v[100:101], v[72:73] op_sel_hi:[0,1]
	v_cvt_pk_bf16_f32 v14, v14, v15
	v_cvt_pk_bf16_f32 v15, v16, v17
	v_pk_mul_f32 v[16:17], v[100:101], v[74:75] op_sel_hi:[0,1]
	v_cvt_pk_bf16_f32 v16, v16, v17
	v_cvt_pk_bf16_f32 v17, v42, v43
	global_load_dwordx4 v[144:147], v[94:95], off offset:64
	v_lshl_add_u64 v[178:179], v[102:103], 0, v[56:57]
	global_load_dwordx4 v[148:151], v[178:179], off
	v_lshl_add_u64 v[180:181], v[102:103], 0, v[58:59]
	global_load_dwordx4 v[152:155], v[180:181], off
	v_lshl_add_u64 v[182:183], v[102:103], 0, v[60:61]
	global_load_dwordx4 v[156:159], v[182:183], off
	v_lshl_add_u64 v[184:185], v[102:103], 0, v[62:63]
	global_load_dwordx4 v[160:163], v[184:185], off
	v_lshl_add_u64 v[186:187], v[102:103], 0, v[64:65]
	global_load_dwordx4 v[164:167], v[186:187], off
	v_lshl_add_u64 v[188:189], v[102:103], 0, v[66:67]
	global_load_dwordx4 v[168:171], v[188:189], off
	v_lshl_add_u64 v[190:191], v[102:103], 0, v[68:69]
	global_load_dwordx4 v[172:175], v[190:191], off
	s_waitcnt vmcnt(7)
	v_mfma_f32_16x16x32_bf16 v[6:9], v[144:147], v[14:17], v[6:9]
	s_waitcnt vmcnt(6)
	v_mfma_f32_16x16x32_bf16 v[10:13], v[148:151], v[14:17], v[10:13]
	s_waitcnt vmcnt(5)
	v_mfma_f32_16x16x32_bf16 v[18:21], v[152:155], v[14:17], v[18:21]
	s_waitcnt vmcnt(4)
	v_mfma_f32_16x16x32_bf16 v[26:29], v[156:159], v[14:17], v[26:29]
	s_waitcnt vmcnt(3)
	v_mfma_f32_16x16x32_bf16 v[22:25], v[160:163], v[14:17], v[22:25]
	s_waitcnt vmcnt(2)
	v_mfma_f32_16x16x32_bf16 v[42:45], v[164:167], v[14:17], v[30:33]
	s_nop 2
	s_waitcnt vmcnt(1)
	v_mfma_f32_16x16x32_bf16 v[46:49], v[168:171], v[14:17], v[34:37]
	v_lshl_add_u64 v[102:103], v[96:97], 0, s[38:39]
	v_lshl_add_u64 v[96:97], v[96:97], 0, s[8:9]
	s_waitcnt vmcnt(0)
	v_mfma_f32_16x16x32_bf16 v[0:3], v[172:175], v[14:17], v[0:3]
	v_mul_f32_e64 v14, v100, v78
	v_mul_f32_e64 v15, v100, v79
	v_pk_mul_f32 v[16:17], v[100:101], v[80:81] op_sel_hi:[0,1]
	v_cvt_pk_bf16_f32 v14, v14, v15
	v_cvt_pk_bf16_f32 v15, v16, v17
	v_pk_mul_f32 v[16:17], v[100:101], v[82:83] op_sel_hi:[0,1]
	v_pk_mul_f32 v[30:31], v[100:101], v[84:85] op_sel_hi:[0,1]
	v_cvt_pk_bf16_f32 v16, v16, v17
	v_cvt_pk_bf16_f32 v17, v30, v31
	global_load_dwordx4 v[144:147], v[94:95], off offset:128
	v_lshl_add_u64 v[178:179], v[102:103], 0, v[56:57]
	global_load_dwordx4 v[148:151], v[178:179], off
	v_lshl_add_u64 v[180:181], v[102:103], 0, v[58:59]
	global_load_dwordx4 v[152:155], v[180:181], off
	v_lshl_add_u64 v[182:183], v[102:103], 0, v[60:61]
	global_load_dwordx4 v[156:159], v[182:183], off
	v_lshl_add_u64 v[184:185], v[102:103], 0, v[62:63]
	global_load_dwordx4 v[160:163], v[184:185], off
	v_lshl_add_u64 v[186:187], v[102:103], 0, v[64:65]
	global_load_dwordx4 v[164:167], v[186:187], off
	v_lshl_add_u64 v[188:189], v[102:103], 0, v[66:67]
	global_load_dwordx4 v[168:171], v[188:189], off
	v_lshl_add_u64 v[190:191], v[102:103], 0, v[68:69]
	global_load_dwordx4 v[172:175], v[190:191], off
	s_waitcnt vmcnt(7)
	v_mfma_f32_16x16x32_bf16 v[6:9], v[144:147], v[14:17], v[6:9]
	s_waitcnt vmcnt(6)
	v_mfma_f32_16x16x32_bf16 v[10:13], v[148:151], v[14:17], v[10:13]
	s_waitcnt vmcnt(5)
	v_mfma_f32_16x16x32_bf16 v[30:33], v[152:155], v[14:17], v[18:21]
	s_nop 2
	s_waitcnt vmcnt(4)
	v_mfma_f32_16x16x32_bf16 v[26:29], v[156:159], v[14:17], v[26:29]
	s_waitcnt vmcnt(3)
	v_mfma_f32_16x16x32_bf16 v[22:25], v[160:163], v[14:17], v[22:25]
	s_waitcnt vmcnt(2)
	v_mfma_f32_16x16x32_bf16 v[34:37], v[164:167], v[14:17], v[42:45]
	s_nop 1
	s_nop 0
	s_waitcnt vmcnt(1)
	v_mfma_f32_16x16x32_bf16 v[18:21], v[168:171], v[14:17], v[46:49]
	s_waitcnt vmcnt(0)
	v_mfma_f32_16x16x32_bf16 v[0:3], v[172:175], v[14:17], v[0:3]
	v_mul_f32_e64 v14, v100, v86
	v_mul_f32_e64 v15, v100, v87
	v_pk_mul_f32 v[16:17], v[100:101], v[88:89] op_sel_hi:[0,1]
	v_cvt_pk_bf16_f32 v14, v14, v15
	v_cvt_pk_bf16_f32 v15, v16, v17
	v_pk_mul_f32 v[16:17], v[100:101], v[90:91] op_sel_hi:[0,1]
	v_pk_mul_f32 v[42:43], v[100:101], v[92:93] op_sel_hi:[0,1]
	v_cvt_pk_bf16_f32 v16, v16, v17
	v_cvt_pk_bf16_f32 v17, v42, v43
	global_load_dwordx4 v[144:147], v[94:95], off offset:192
	v_lshl_add_u64 v[178:179], v[96:97], 0, v[56:57]
	global_load_dwordx4 v[148:151], v[178:179], off
	v_lshl_add_u64 v[180:181], v[96:97], 0, v[58:59]
	global_load_dwordx4 v[152:155], v[180:181], off
	v_lshl_add_u64 v[182:183], v[96:97], 0, v[60:61]
	global_load_dwordx4 v[156:159], v[182:183], off
	v_lshl_add_u64 v[184:185], v[96:97], 0, v[62:63]
	global_load_dwordx4 v[160:163], v[184:185], off
	v_lshl_add_u64 v[186:187], v[96:97], 0, v[64:65]
	global_load_dwordx4 v[164:167], v[186:187], off
	v_lshl_add_u64 v[188:189], v[96:97], 0, v[66:67]
	global_load_dwordx4 v[168:171], v[188:189], off
	v_lshl_add_u64 v[190:191], v[96:97], 0, v[68:69]
	global_load_dwordx4 v[172:175], v[190:191], off
	s_waitcnt vmcnt(7)
	v_mfma_f32_16x16x32_bf16 v[6:9], v[144:147], v[14:17], v[6:9]
	s_waitcnt vmcnt(6)
	v_mfma_f32_16x16x32_bf16 v[10:13], v[148:151], v[14:17], v[10:13]
	s_waitcnt vmcnt(5)
	v_mfma_f32_16x16x32_bf16 v[30:33], v[152:155], v[14:17], v[30:33]
	s_waitcnt vmcnt(4)
	v_mfma_f32_16x16x32_bf16 v[26:29], v[156:159], v[14:17], v[26:29]
	s_waitcnt vmcnt(3)
	v_mfma_f32_16x16x32_bf16 v[22:25], v[160:163], v[14:17], v[22:25]
	s_waitcnt vmcnt(2)
	v_mfma_f32_16x16x32_bf16 v[46:49], v[164:167], v[14:17], v[34:37]
	s_nop 2
	s_waitcnt vmcnt(1)
	v_mfma_f32_16x16x32_bf16 v[42:45], v[168:171], v[14:17], v[18:21]
	s_nop 2
	s_waitcnt vmcnt(0)
	v_mfma_f32_16x16x32_bf16 v[0:3], v[172:175], v[14:17], v[0:3]
	s_cbranch_vccnz .LBB0_3542
	v_mov_b32_e32 v14, v6
	v_mov_b32_e32 v15, v10
	v_mov_b32_e32 v16, v7
	v_mov_b32_e32 v17, v11
	v_pk_add_f32 v[14:15], v[14:15], v[16:17]
	v_mov_b32_e32 v16, v8
	v_mov_b32_e32 v17, v12
	v_pk_add_f32 v[14:15], v[16:17], v[14:15]
	v_mov_b32_e32 v16, v9
	v_mov_b32_e32 v17, v13
	v_pk_add_f32 v[14:15], v[16:17], v[14:15]
	v_mov_b32_e32 v16, v31
	v_add_f32_e32 v4, 0, v14
	v_add_f32_e32 v4, v4, v15
	v_mov_b32_e32 v14, v30
	v_mov_b32_e32 v15, v26
	v_mov_b32_e32 v17, v27
	v_pk_add_f32 v[14:15], v[14:15], v[16:17]
	v_mov_b32_e32 v16, v32
	v_mov_b32_e32 v17, v28
	v_pk_add_f32 v[14:15], v[16:17], v[14:15]
	v_mov_b32_e32 v16, v33
	v_mov_b32_e32 v17, v29
	v_pk_add_f32 v[14:15], v[16:17], v[14:15]
	v_mov_b32_e32 v16, v23
	v_add_f32_e32 v4, v4, v14
	v_add_f32_e32 v4, v4, v15
	v_mov_b32_e32 v14, v22
	v_mov_b32_e32 v15, v46
	v_mov_b32_e32 v17, v47
	v_pk_add_f32 v[14:15], v[14:15], v[16:17]
	v_mov_b32_e32 v16, v24
	v_mov_b32_e32 v17, v48
	v_pk_add_f32 v[14:15], v[16:17], v[14:15]
	v_mov_b32_e32 v16, v25
	v_mov_b32_e32 v17, v49
	v_pk_add_f32 v[14:15], v[16:17], v[14:15]
	v_mov_b32_e32 v16, v43
	v_add_f32_e32 v4, v4, v14
	v_add_f32_e32 v4, v4, v15
	v_mov_b32_e32 v14, v42
	v_mov_b32_e32 v15, v0
	v_mov_b32_e32 v17, v1
	v_pk_add_f32 v[14:15], v[14:15], v[16:17]
	v_mov_b32_e32 v16, v44
	v_mov_b32_e32 v17, v2
	v_pk_add_f32 v[14:15], v[16:17], v[14:15]
	v_mov_b32_e32 v16, v45
	v_mov_b32_e32 v17, v3
	v_pk_add_f32 v[14:15], v[16:17], v[14:15]
	v_or3_b32 v110, v141, s6, v110
	v_add_f32_e32 v4, v4, v14
	v_add_f32_e32 v4, v4, v15
	v_and_b32_e32 v15, 64, v238
	v_xor_b32_e32 v14, 16, v238
	v_add_u32_e32 v20, 64, v15
	v_cmp_lt_i32_e32 vcc, v14, v20
	v_lshlrev_b64 v[16:17], 1, v[110:111]
	s_mov_b32 s0, 0x800000
	v_cndmask_b32_e32 v14, v238, v14, vcc
	v_lshlrev_b32_e32 v70, 2, v14
	v_lshl_add_u64 v[14:15], s[46:47], 0, v[16:17]
	global_load_dwordx2 v[18:19], v[14:15], off
	ds_bpermute_b32 v21, v70, v4
	v_xor_b32_e32 v14, 32, v238
	v_cmp_lt_i32_e32 vcc, v14, v20
	v_lshl_add_u64 v[16:17], s[48:49], 0, v[16:17]
	s_waitcnt lgkmcnt(0)
	v_add_f32_e32 v4, v4, v21
	v_cndmask_b32_e32 v14, v238, v14, vcc
	v_lshlrev_b32_e32 v71, 2, v14
	ds_bpermute_b32 v14, v71, v4
	s_waitcnt lgkmcnt(0)
	v_add_f32_e32 v4, v4, v14
	v_mul_f32_e32 v4, 0x3c000000, v4
	v_pk_add_f32 v[6:7], v[6:7], v[4:5] op_sel_hi:[1,0] neg_lo:[0,1] neg_hi:[0,1]
	v_pk_add_f32 v[8:9], v[8:9], v[4:5] op_sel_hi:[1,0] neg_lo:[0,1] neg_hi:[0,1]
	v_pk_mul_f32 v[36:37], v[6:7], v[6:7]
	v_pk_add_f32 v[14:15], v[0:1], v[4:5] op_sel_hi:[1,0] neg_lo:[0,1] neg_hi:[0,1]
	v_pk_add_f32 v[0:1], v[2:3], v[4:5] op_sel_hi:[1,0] neg_lo:[0,1] neg_hi:[0,1]
	v_pk_mul_f32 v[34:35], v[8:9], v[8:9]
	v_pk_add_f32 v[12:13], v[12:13], v[4:5] op_sel_hi:[1,0] neg_lo:[0,1] neg_hi:[0,1]
	v_pk_add_f32 v[10:11], v[10:11], v[4:5] op_sel_hi:[1,0] neg_lo:[0,1] neg_hi:[0,1]
	v_pk_add_f32 v[32:33], v[32:33], v[4:5] op_sel_hi:[1,0] neg_lo:[0,1] neg_hi:[0,1]
	v_pk_add_f32 v[30:31], v[30:31], v[4:5] op_sel_hi:[1,0] neg_lo:[0,1] neg_hi:[0,1]
	v_pk_add_f32 v[28:29], v[28:29], v[4:5] op_sel_hi:[1,0] neg_lo:[0,1] neg_hi:[0,1]
	v_pk_add_f32 v[26:27], v[26:27], v[4:5] op_sel_hi:[1,0] neg_lo:[0,1] neg_hi:[0,1]
	v_pk_add_f32 v[24:25], v[24:25], v[4:5] op_sel_hi:[1,0] neg_lo:[0,1] neg_hi:[0,1]
	v_pk_add_f32 v[22:23], v[22:23], v[4:5] op_sel_hi:[1,0] neg_lo:[0,1] neg_hi:[0,1]
	v_pk_add_f32 v[48:49], v[48:49], v[4:5] op_sel_hi:[1,0] neg_lo:[0,1] neg_hi:[0,1]
	v_pk_add_f32 v[46:47], v[46:47], v[4:5] op_sel_hi:[1,0] neg_lo:[0,1] neg_hi:[0,1]
	v_pk_add_f32 v[44:45], v[44:45], v[4:5] op_sel_hi:[1,0] neg_lo:[0,1] neg_hi:[0,1]
	v_pk_add_f32 v[42:43], v[42:43], v[4:5] op_sel_hi:[1,0] neg_lo:[0,1] neg_hi:[0,1]
	v_add_f32_e32 v4, v36, v37
	v_add_f32_e32 v4, v34, v4
	v_pk_mul_f32 v[40:41], v[10:11], v[10:11]
	v_add_f32_e32 v4, v35, v4
	v_add_f32_e32 v4, v40, v4
	v_pk_mul_f32 v[38:39], v[12:13], v[12:13]
	v_add_f32_e32 v4, v41, v4
	v_add_f32_e32 v4, v38, v4
	v_pk_mul_f32 v[52:53], v[30:31], v[30:31]
	v_add_f32_e32 v4, v39, v4
	v_add_f32_e32 v4, v52, v4
	v_pk_mul_f32 v[50:51], v[32:33], v[32:33]
	v_add_f32_e32 v4, v53, v4
	v_add_f32_e32 v4, v50, v4
	v_pk_mul_f32 v[56:57], v[26:27], v[26:27]
	v_add_f32_e32 v4, v51, v4
	v_add_f32_e32 v4, v56, v4
	v_pk_mul_f32 v[54:55], v[28:29], v[28:29]
	v_add_f32_e32 v4, v57, v4
	v_add_f32_e32 v4, v54, v4
	v_pk_mul_f32 v[60:61], v[22:23], v[22:23]
	v_add_f32_e32 v4, v55, v4
	v_add_f32_e32 v4, v60, v4
	v_pk_mul_f32 v[58:59], v[24:25], v[24:25]
	v_add_f32_e32 v4, v61, v4
	v_add_f32_e32 v4, v58, v4
	v_pk_mul_f32 v[64:65], v[46:47], v[46:47]
	v_add_f32_e32 v4, v59, v4
	v_add_f32_e32 v4, v64, v4
	v_pk_mul_f32 v[62:63], v[48:49], v[48:49]
	v_add_f32_e32 v4, v65, v4
	v_add_f32_e32 v4, v62, v4
	v_pk_mul_f32 v[68:69], v[42:43], v[42:43]
	v_add_f32_e32 v4, v63, v4
	v_add_f32_e32 v4, v68, v4
	v_pk_mul_f32 v[66:67], v[44:45], v[44:45]
	v_add_f32_e32 v4, v69, v4
	v_add_f32_e32 v4, v66, v4
	v_pk_mul_f32 v[20:21], v[14:15], v[14:15]
	v_add_f32_e32 v4, v67, v4
	v_add_f32_e32 v4, v20, v4
	v_pk_mul_f32 v[2:3], v[0:1], v[0:1]
	v_add_f32_e32 v4, v21, v4
	v_add_f32_e32 v2, v2, v4
	v_add_f32_e32 v4, v3, v2
	ds_bpermute_b32 v20, v70, v4
	s_waitcnt vmcnt(0)
	v_lshlrev_b32_e32 v2, 16, v18
	v_and_b32_e32 v3, 0xffff0000, v18
	v_lshlrev_b32_e32 v18, 16, v19
	v_and_b32_e32 v19, 0xffff0000, v19
	s_waitcnt lgkmcnt(0)
	v_add_f32_e32 v4, v4, v20
	ds_bpermute_b32 v21, v71, v4
	v_or_b32_e32 v20, 16, v110
	s_waitcnt lgkmcnt(0)
	v_add_f32_e32 v4, v4, v21
	v_fmamk_f32 v4, v4, 0x3c000000, v236
	v_mul_f32_e32 v21, 0x4b800000, v4
	v_cmp_gt_f32_e32 vcc, s0, v4
	s_nop 1
	v_cndmask_b32_e32 v4, v4, v21, vcc
	v_rsq_f32_e32 v4, v4
	v_mov_b32_e32 v21, v111
	v_lshlrev_b64 v[20:21], 1, v[20:21]
	v_lshl_add_u64 v[34:35], s[46:47], 0, v[20:21]
	v_mul_f32_e32 v36, 0x45800000, v4
	v_cndmask_b32_e32 v4, v4, v36, vcc
	v_pk_mul_f32 v[6:7], v[6:7], v[4:5] op_sel_hi:[1,0]
	v_pk_mul_f32 v[10:11], v[10:11], v[4:5] op_sel_hi:[1,0]
	v_pk_mul_f32 v[2:3], v[6:7], v[2:3]
	v_pk_mul_f32 v[6:7], v[8:9], v[4:5] op_sel_hi:[1,0]
	v_cvt_pk_bf16_f32 v2, v2, v3
	v_pk_mul_f32 v[6:7], v[6:7], v[18:19]
	v_pk_mul_f32 v[12:13], v[12:13], v[4:5] op_sel_hi:[1,0]
	v_cvt_pk_bf16_f32 v3, v6, v7
	global_store_dwordx2 v[16:17], v[2:3], off
	global_load_dwordx2 v[2:3], v[34:35], off
	v_mov_b32_e32 v7, v111
	v_or_b32_e32 v6, 32, v110
	v_lshlrev_b64 v[6:7], 1, v[6:7]
	v_lshl_add_u64 v[8:9], s[48:49], 0, v[20:21]
	v_lshl_add_u64 v[16:17], s[46:47], 0, v[6:7]
	v_lshl_add_u64 v[6:7], s[48:49], 0, v[6:7]
	v_pk_mul_f32 v[0:1], v[0:1], v[4:5] op_sel_hi:[1,0]
	s_waitcnt vmcnt(0)
	v_lshlrev_b32_e32 v18, 16, v2
	v_and_b32_e32 v19, 0xffff0000, v2
	v_lshlrev_b32_e32 v2, 16, v3
	v_and_b32_e32 v3, 0xffff0000, v3
	v_pk_mul_f32 v[10:11], v[10:11], v[18:19]
	v_pk_mul_f32 v[2:3], v[12:13], v[2:3]
	v_cvt_pk_bf16_f32 v10, v10, v11
	v_cvt_pk_bf16_f32 v11, v2, v3
	global_store_dwordx2 v[8:9], v[10:11], off
	global_load_dwordx2 v[2:3], v[16:17], off
	v_pk_mul_f32 v[12:13], v[30:31], v[4:5] op_sel_hi:[1,0]
	v_pk_mul_f32 v[16:17], v[32:33], v[4:5] op_sel_hi:[1,0]
	v_mov_b32_e32 v9, v111
	v_or_b32_e32 v8, 48, v110
	v_lshlrev_b64 v[8:9], 1, v[8:9]
	v_lshl_add_u64 v[10:11], s[46:47], 0, v[8:9]
	v_lshl_add_u64 v[8:9], s[48:49], 0, v[8:9]
	s_waitcnt vmcnt(0)
	v_lshlrev_b32_e32 v18, 16, v2
	v_and_b32_e32 v19, 0xffff0000, v2
	v_lshlrev_b32_e32 v2, 16, v3
	v_and_b32_e32 v3, 0xffff0000, v3
	v_pk_mul_f32 v[12:13], v[12:13], v[18:19]
	v_pk_mul_f32 v[2:3], v[16:17], v[2:3]
	v_cvt_pk_bf16_f32 v12, v12, v13
	v_cvt_pk_bf16_f32 v13, v2, v3
	global_store_dwordx2 v[6:7], v[12:13], off
	global_load_dwordx2 v[2:3], v[10:11], off
	v_pk_mul_f32 v[12:13], v[26:27], v[4:5] op_sel_hi:[1,0]
	v_pk_mul_f32 v[16:17], v[28:29], v[4:5] op_sel_hi:[1,0]
	v_mov_b32_e32 v7, v111
	v_or_b32_e32 v6, 64, v110
	v_lshlrev_b64 v[6:7], 1, v[6:7]
	v_lshl_add_u64 v[10:11], s[46:47], 0, v[6:7]
	v_lshl_add_u64 v[6:7], s[48:49], 0, v[6:7]
	s_waitcnt vmcnt(0)
	v_lshlrev_b32_e32 v18, 16, v2
	v_and_b32_e32 v19, 0xffff0000, v2
	v_lshlrev_b32_e32 v2, 16, v3
	v_and_b32_e32 v3, 0xffff0000, v3
	v_pk_mul_f32 v[12:13], v[12:13], v[18:19]
	v_pk_mul_f32 v[2:3], v[16:17], v[2:3]
	v_cvt_pk_bf16_f32 v12, v12, v13
	v_cvt_pk_bf16_f32 v13, v2, v3
	global_store_dwordx2 v[8:9], v[12:13], off
	global_load_dwordx2 v[2:3], v[10:11], off
	v_pk_mul_f32 v[12:13], v[22:23], v[4:5] op_sel_hi:[1,0]
	v_pk_mul_f32 v[16:17], v[24:25], v[4:5] op_sel_hi:[1,0]
	v_mov_b32_e32 v9, v111
	v_or_b32_e32 v8, 0x50, v110
	v_lshlrev_b64 v[8:9], 1, v[8:9]
	v_lshl_add_u64 v[10:11], s[46:47], 0, v[8:9]
	v_lshl_add_u64 v[8:9], s[48:49], 0, v[8:9]
	s_waitcnt vmcnt(0)
	v_lshlrev_b32_e32 v18, 16, v2
	v_and_b32_e32 v19, 0xffff0000, v2
	v_lshlrev_b32_e32 v2, 16, v3
	v_and_b32_e32 v3, 0xffff0000, v3
	v_pk_mul_f32 v[12:13], v[12:13], v[18:19]
	v_pk_mul_f32 v[2:3], v[16:17], v[2:3]
	v_cvt_pk_bf16_f32 v12, v12, v13
	v_cvt_pk_bf16_f32 v13, v2, v3
	global_store_dwordx2 v[6:7], v[12:13], off
	global_load_dwordx2 v[2:3], v[10:11], off
	v_pk_mul_f32 v[12:13], v[46:47], v[4:5] op_sel_hi:[1,0]
	v_pk_mul_f32 v[16:17], v[48:49], v[4:5] op_sel_hi:[1,0]
	v_mov_b32_e32 v7, v111
	v_or_b32_e32 v6, 0x60, v110
	v_lshlrev_b64 v[6:7], 1, v[6:7]
	v_lshl_add_u64 v[10:11], s[46:47], 0, v[6:7]
	v_or_b32_e32 v110, 0x70, v110
	v_lshl_add_u64 v[6:7], s[48:49], 0, v[6:7]
	s_waitcnt vmcnt(0)
	v_lshlrev_b32_e32 v18, 16, v2
	v_and_b32_e32 v19, 0xffff0000, v2
	v_lshlrev_b32_e32 v2, 16, v3
	v_and_b32_e32 v3, 0xffff0000, v3
	v_pk_mul_f32 v[12:13], v[12:13], v[18:19]
	v_pk_mul_f32 v[2:3], v[16:17], v[2:3]
	v_cvt_pk_bf16_f32 v12, v12, v13
	v_cvt_pk_bf16_f32 v13, v2, v3
	global_store_dwordx2 v[8:9], v[12:13], off
	global_load_dwordx2 v[2:3], v[10:11], off
	v_pk_mul_f32 v[12:13], v[42:43], v[4:5] op_sel_hi:[1,0]
	v_pk_mul_f32 v[16:17], v[44:45], v[4:5] op_sel_hi:[1,0]
	v_lshlrev_b64 v[8:9], 1, v[110:111]
	v_lshl_add_u64 v[10:11], s[46:47], 0, v[8:9]
	s_waitcnt vmcnt(0)
	v_lshlrev_b32_e32 v18, 16, v2
	v_and_b32_e32 v19, 0xffff0000, v2
	v_lshlrev_b32_e32 v2, 16, v3
	v_and_b32_e32 v3, 0xffff0000, v3
	v_pk_mul_f32 v[12:13], v[12:13], v[18:19]
	v_pk_mul_f32 v[2:3], v[16:17], v[2:3]
	v_cvt_pk_bf16_f32 v12, v12, v13
	v_cvt_pk_bf16_f32 v13, v2, v3
	global_store_dwordx2 v[6:7], v[12:13], off
	global_load_dwordx2 v[2:3], v[10:11], off
	v_pk_mul_f32 v[6:7], v[14:15], v[4:5] op_sel_hi:[1,0]
	s_waitcnt vmcnt(0)
	v_lshlrev_b32_e32 v10, 16, v2
	v_and_b32_e32 v11, 0xffff0000, v2
	v_lshlrev_b32_e32 v2, 16, v3
	v_and_b32_e32 v3, 0xffff0000, v3
	v_pk_mul_f32 v[6:7], v[6:7], v[10:11]
	v_pk_mul_f32 v[0:1], v[0:1], v[2:3]
	v_cvt_pk_bf16_f32 v2, v6, v7
	v_cvt_pk_bf16_f32 v3, v0, v1
	v_lshl_add_u64 v[0:1], s[48:49], 0, v[8:9]
	global_store_dwordx2 v[0:1], v[2:3], off

.LBB0_3871:
	s_cmp_gt_u32 s67, 18
	s_cbranch_scc0 .LBB0_3921
	s_waitcnt vmcnt(0)
	s_waitcnt vmcnt(63) expcnt(7) lgkmcnt(15)
	s_barrier
	s_mov_b64 s[4:5], exec
	v_readlane_b32 s2, v251, 3
	v_readlane_b32 s3, v251, 4
	s_and_b64 s[2:3], s[4:5], s[2:3]
	s_mov_b64 exec, s[2:3]
	s_cbranch_execz .Lxb_done_18
	v_mov_b32_e32 v0, 0
	s_waitcnt vmcnt(0) expcnt(0) lgkmcnt(0)
	ds_read_b32 v2, v0
	ds_read_b32 v1, v0 offset:4
	v_readlane_b32 s0, v251, 2
	v_readlane_b32 s6, v251, 5
	v_readlane_b32 s7, v251, 6
	s_lshl_b32 s0, s0, 8
	s_add_u32 s8, s6, s0
	s_addc_u32 s9, s7, 0
	v_mov_b32_e32 v3, 1
	v_mov_b32_e32 v4, 0x1000
	s_nop 4
	global_atomic_add v3, v4, v3, s[8:9] offset:1024 sc0
	buffer_inv sc1
	s_sub_u32 s10, 17, s66
	s_add_u32 s11, s10, 1
	s_waitcnt lgkmcnt(0)
	v_readfirstlane_b32 s12, v2
	v_readfirstlane_b32 s13, v1
	s_mul_i32 s14, s12, s11
	s_mul_i32 s15, s13, s11
	s_waitcnt vmcnt(0)
	v_readfirstlane_b32 s16, v3
	s_add_u32 s16, s16, 1
	s_cmp_lg_u32 s16, s14
	s_cbranch_scc1 .Lxb_wait_18
	buffer_wbl2 sc1
	s_waitcnt vmcnt(0)
	v_mov_b32_e32 v3, 1
	v_mov_b32_e32 v4, 0x7f000
	global_atomic_add v3, v4, v3, s[30:31] offset:1024 sc0
	s_waitcnt vmcnt(0)
	v_readfirstlane_b32 s16, v3
	s_add_u32 s16, s16, 1
	s_cmp_lg_u32 s16, s15
	s_cbranch_scc1 .Lxb_wait_18
	v_mov_b32_e32 v3, 1
	v_mov_b32_e32 v4, 0x2400
	global_atomic_add v4, v3, s[6:7]
	v_add_u32_e32 v4, 0x100, v4
	global_atomic_add v4, v3, s[6:7]
	v_add_u32_e32 v4, 0x100, v4
	global_atomic_add v4, v3, s[6:7]
	v_add_u32_e32 v4, 0x100, v4
	global_atomic_add v4, v3, s[6:7]
	v_add_u32_e32 v4, 0x100, v4
	global_atomic_add v4, v3, s[6:7]
	v_add_u32_e32 v4, 0x100, v4
	global_atomic_add v4, v3, s[6:7]
	v_add_u32_e32 v4, 0x100, v4
	global_atomic_add v4, v3, s[6:7]
	v_add_u32_e32 v4, 0x100, v4
	global_atomic_add v4, v3, s[6:7]
	v_add_u32_e32 v4, 0x100, v4
	global_atomic_add v4, v3, s[6:7]
	v_add_u32_e32 v4, 0x100, v4
	global_atomic_add v4, v3, s[6:7]
	v_add_u32_e32 v4, 0x100, v4
	global_atomic_add v4, v3, s[6:7]
	v_add_u32_e32 v4, 0x100, v4
	global_atomic_add v4, v3, s[6:7]
	v_add_u32_e32 v4, 0x100, v4
	global_atomic_add v4, v3, s[6:7]
	v_add_u32_e32 v4, 0x100, v4
	global_atomic_add v4, v3, s[6:7]
	v_add_u32_e32 v4, 0x100, v4
	global_atomic_add v4, v3, s[6:7]
	v_add_u32_e32 v4, 0x100, v4
	global_atomic_add v4, v3, s[6:7]
	v_add_u32_e32 v4, 0x100, v4
	v_mov_b32_e32 v4, 0x7f000
	global_atomic_add v4, v3, s[30:31] offset:1280

.Lxb_done_18:
	s_or_b64 exec, exec, s[4:5]
	s_waitcnt lgkmcnt(0)
	s_barrier
.LBB0_3921:
	s_cmp_gt_i32 s66, 18
	s_cselect_b64 s[0:1], -1, 0
	s_cmp_lt_i32 s67, 19
	s_cselect_b64 s[2:3], -1, 0
	s_or_b64 s[0:1], s[0:1], s[2:3]
	s_and_b64 vcc, exec, s[0:1]
	s_cbranch_vccnz .LBB0_3981
	s_and_b32 s12, s78, 7
	s_lshr_b32 s2, s78, 3
	s_ashr_i32 s3, s64, 3
	s_cmpk_lt_u32 s78, 0x200
	s_cselect_b64 s[0:1], -1, 0
	s_add_u32 s4, s30, 0xab93e00
	s_addc_u32 s5, s31, 0
	s_add_u32 s6, s30, 0x4313e00
	s_addc_u32 s7, s31, 0
	s_add_u32 s13, s30, 0x5393e00
	v_cndmask_b32_e64 v0, 0, 1, s[0:1]
	s_addc_u32 s14, s31, 0
	s_lshl_b32 s15, s12, 3
	s_mov_b32 s16, 0
	s_lshl_b32 s17, s12, 10
	v_cmp_ne_u32_e64 s[0:1], 1, v0
	v_mov_b32_e32 v97, 0
	s_mov_b32 s18, 0x10000
	s_mov_b32 s19, 0x20000
	s_mov_b32 s20, 0x30000
	s_movk_i32 s21, 0x90
	s_mov_b32 s22, 0xfffffc0
	s_mov_b32 s23, 0xab93000
	s_mov_b32 s24, 0xaba3000
	s_mov_b32 s25, 0xabb3000
	s_mov_b32 s26, 0xabc3000
	s_mov_b32 s27, 0x4313000
	s_mov_b32 s33, 0x4323000
	s_mov_b32 s34, 0x4333000
	s_mov_b32 s35, 0x4343000
	s_mov_b64 s[8:9], 0x100
	s_movk_i32 s36, 0x110
	s_movk_i32 s37, 0x2c00
	s_branch .LBB0_3924
